# split128 + sample attention group loop double-buffered through wave-private LDS via global_load_lds
# baseline (speedup 1.0000x reference)
; __device__ __forceinline__ void attn_sample_phase(const bf16* QKVb, const float* ck, const float* cv, const float* out, bf16* SPART, float2* SML, int gw, int NGW, int lane) {
;     const int l16 = lane & 15, hq = lane >> 4;
;     for (int item = gw; item < DBATCH * SA_CH; item += NGW) {
;         const int b = item / SA_CH, c = item % SA_CH;
;         f32x4 q[4][2], o[4][2]; float m[4][2], l[4][2];
; #pragma unroll
;         for (int i = 0; i < 4; ++i)
; #pragma unroll
;             for (int u = 0; u < 2; ++u) {
;                 { const uint2 qq = *(const uint2*)(QKVb + (size_t)(MP + b * 4 + i) * INW + C_QA + (4 * u + hq) * 64 + 4 * l16); q[i][u] = (f32x4){bf_lo(qq.x), bf_hi(qq.x), bf_lo(qq.y), bf_hi(qq.y)}; }
;                 o[i][u] = (f32x4){0.f, 0.f, 0.f, 0.f}; m[i][u] = -1e30f; l[i][u] = 0.f;
;             }
.Lsa_entry:
	s_cmpk_gt_i32 s0, 0x77f
	s_cbranch_scc1 .LBB0_1150
	v_readlane_b32 s29, v254, 34
	s_nop 3
	s_lshl_b32 s29, s29, 14
	v_lshl_add_u32 v202, v162, 4, s29
	v_mov_b32_e32 v2, 0
	v_readlane_b32 s2, v254, 55
	s_add_u32 s19, s88, 0x4a20000
	s_waitcnt vmcnt(0)
	v_lshrrev_b32_e32 v100, 4, v162
	v_mov_b32_e32 v135, v2
	v_readlane_b32 s3, v254, 56
	s_addc_u32 s20, s89, 0
	s_add_u32 s21, s88, 0x4b20000
	v_lshl_add_u64 v[4:5], s[2:3], 0, v[134:135]
	v_lshlrev_b32_e32 v6, 7, v100
	v_mov_b32_e32 v7, v2
	v_lshlrev_b32_e32 v102, 2, v162
	s_addc_u32 s22, s89, 0
	v_lshl_add_u64 v[104:105], s[14:15], 0, v[134:135]
	v_cmp_ne_u32_e64 s[4:5], 0, v167
	v_lshl_add_u64 v[106:107], v[4:5], 0, v[6:7]
	v_mov_b32_e32 v101, 0x1800
	s_branch .LBB0_1076

; __device__ __forceinline__ void attn_sample_phase(const bf16* QKVb, const float* ck, const float* cv, const float* out, bf16* SPART, float2* SML, int gw, int NGW, int lane) {
;     ...
;         const int b = item / SA_CH, c = item % SA_CH;
;         f32x4 q[4][2], o[4][2]; float m[4][2], l[4][2];
; #pragma unroll
;         for (int i = 0; i < 4; ++i)
; #pragma unroll
;             for (int u = 0; u < 2; ++u) {
;                 { const uint2 qq = *(const uint2*)(QKVb + (size_t)(MP + b * 4 + i) * INW + C_QA + (4 * u + hq) * 64 + 4 * l16); q[i][u] = (f32x4){bf_lo(qq.x), bf_hi(qq.x), bf_lo(qq.y), bf_hi(qq.y)}; }
;                 o[i][u] = (f32x4){0.f, 0.f, 0.f, 0.f}; m[i][u] = -1e30f; l[i][u] = 0.f;
;             }
;         for (int g = 0; g < SA_KPC / 4; ++g) {
;             f32x4 kx[4][2], vx[4][2]; int ee[4];
; #pragma unroll
;             for (int t = 0; t < 4; ++t) {
;                 const float *kr, *vr; sa_rows(c * SA_KPC + g * 4 + t, b, ck, cv, out, kr, vr, ee[t]);
;                 kx[t][0] = __builtin_nontemporal_load((const f32x4*)(kr + 4 * lane)); kx[t][1] = __builtin_nontemporal_load((const f32x4*)(kr + 256 + 4 * lane));
;                 vx[t][0] = __builtin_nontemporal_load((const f32x4*)(vr + 4 * lane)); vx[t][1] = __builtin_nontemporal_load((const f32x4*)(vr + 256 + 4 * lane));
.LBB0_1076:
	s_mul_hi_i32 s1, s0, 0x88888889
	s_add_i32 s1, s1, s0
	s_lshr_b32 s2, s1, 31
	s_ashr_i32 s1, s1, 3
	s_add_i32 s6, s1, s2
	s_lshl_b32 s8, s6, 2
	s_add_i32 s1, s8, 0x4000
	v_mad_i64_i32 v[4:5], s[2:3], s1, v101, v[106:107]
	s_add_i32 s1, s8, 0x4001
	global_load_dwordx2 v[36:37], v[4:5], off
	global_load_dwordx2 v[38:39], v[4:5], off offset:512
	v_mad_i64_i32 v[4:5], s[2:3], s1, v101, v[106:107]
	s_add_i32 s1, s8, 0x4002
	global_load_dwordx2 v[40:41], v[4:5], off
	global_load_dwordx2 v[42:43], v[4:5], off offset:512
	v_mad_i64_i32 v[4:5], s[2:3], s1, v101, v[106:107]
	s_add_i32 s1, s8, 0x4003
	global_load_dwordx2 v[44:45], v[4:5], off
	global_load_dwordx2 v[46:47], v[4:5], off offset:512
	v_mad_i64_i32 v[4:5], s[2:3], s1, v101, v[106:107]
	global_load_dwordx2 v[48:49], v[4:5], off
	global_load_dwordx2 v[50:51], v[4:5], off offset:512
	v_mov_b32_e32 v4, v2
	v_mov_b32_e32 v5, v2
	s_mul_i32 s2, s0, 0xf0
	v_mov_b32_e32 v3, v2
	v_mov_b64_e32 v[34:35], v[4:5]
	v_mov_b64_e32 v[30:31], v[4:5]
	v_mov_b64_e32 v[26:27], v[4:5]
	v_mov_b64_e32 v[22:23], v[4:5]
	v_mov_b64_e32 v[18:19], v[4:5]
	v_mov_b64_e32 v[14:15], v[4:5]
	v_mov_b64_e32 v[10:11], v[4:5]
	s_mul_i32 s3, s6, 15
	s_mul_i32 s9, s6, 0xe10
	v_mov_b32_e32 v157, 0xf149f2ca
	v_mov_b64_e32 v[32:33], v[2:3]
	v_mov_b64_e32 v[28:29], v[2:3]
	v_mov_b64_e32 v[24:25], v[2:3]
	v_mov_b64_e32 v[20:21], v[2:3]
	v_mov_b64_e32 v[16:17], v[2:3]
	v_mov_b64_e32 v[12:13], v[2:3]
	v_mov_b64_e32 v[8:9], v[2:3]
	v_mov_b64_e32 v[6:7], v[4:5]
	s_ashr_i32 s7, s6, 31
	s_sub_i32 s24, s0, s3
	s_sub_i32 s2, s2, s9
	s_mov_b32 s1, 0
	v_mov_b32_e32 v156, 0
	v_mov_b32_e32 v160, 0
	v_mov_b32_e32 v168, 0
	v_mov_b32_e32 v152, 0
	v_mov_b64_e32 v[4:5], v[2:3]
	v_mov_b32_e32 v161, v157
	v_mov_b32_e32 v169, v157
	v_mov_b32_e32 v153, v157
	s_lshl_b64 s[6:7], s[6:7], 20
	s_or_b32 s23, s8, 3
	s_mul_i32 s24, s24, 60
	s_add_i32 s25, s2, 0x7ffff7f0
	v_mov_b32_e32 v170, 0
	v_mov_b32_e32 v171, v157
	v_mov_b32_e32 v154, 0
	v_mov_b32_e32 v155, v157
	v_mov_b32_e32 v172, 0
	v_mov_b32_e32 v173, v157
	v_mov_b32_e32 v158, 0
	v_mov_b32_e32 v159, v157
	s_waitcnt vmcnt(7)
	v_lshlrev_b32_e32 v108, 16, v36
	v_and_b32_e32 v109, 0xffff0000, v36
	v_lshlrev_b32_e32 v110, 16, v37
	v_and_b32_e32 v111, 0xffff0000, v37
	s_waitcnt vmcnt(6)
	v_lshlrev_b32_e32 v112, 16, v38
	v_and_b32_e32 v113, 0xffff0000, v38
	v_lshlrev_b32_e32 v114, 16, v39
	v_and_b32_e32 v115, 0xffff0000, v39
	s_waitcnt vmcnt(5)
	v_lshlrev_b32_e32 v116, 16, v40
	v_and_b32_e32 v117, 0xffff0000, v40
	v_lshlrev_b32_e32 v118, 16, v41
	v_and_b32_e32 v119, 0xffff0000, v41
	s_waitcnt vmcnt(4)
	v_lshlrev_b32_e32 v120, 16, v42
	v_and_b32_e32 v121, 0xffff0000, v42
	v_lshlrev_b32_e32 v122, 16, v43
	v_and_b32_e32 v123, 0xffff0000, v43
	s_waitcnt vmcnt(3)
	v_lshlrev_b32_e32 v124, 16, v44
	v_and_b32_e32 v125, 0xffff0000, v44
	v_lshlrev_b32_e32 v126, 16, v45
	v_and_b32_e32 v127, 0xffff0000, v45
	s_waitcnt vmcnt(2)
	v_lshlrev_b32_e32 v128, 16, v46
	v_and_b32_e32 v129, 0xffff0000, v46
	v_lshlrev_b32_e32 v142, 16, v47
	v_and_b32_e32 v143, 0xffff0000, v47
	s_waitcnt vmcnt(1)
	v_lshlrev_b32_e32 v144, 16, v48
	v_and_b32_e32 v145, 0xffff0000, v48
	v_lshlrev_b32_e32 v146, 16, v49
	v_and_b32_e32 v147, 0xffff0000, v49
	s_waitcnt vmcnt(0)
	v_lshlrev_b32_e32 v148, 16, v50
	v_and_b32_e32 v149, 0xffff0000, v50
	v_lshlrev_b32_e32 v150, 16, v51
	v_and_b32_e32 v151, 0xffff0000, v51
	s_and_b32 s28, s25, 0x7ffffff0
	s_add_i32 s26, s24, s1
	s_add_i32 s2, s28, 0x210
	s_cmpk_lt_i32 s26, 0x204
	s_cselect_b32 s27, s26, s2
	s_cmp_gt_i32 s27, 3
	s_mov_b64 s[12:13], -1
	s_cbranch_scc0 .Lsa0_1080
	s_sub_i32 s2, 0x803, s27
	s_ashr_i32 s3, s2, 31
	s_lshl_b64 s[2:3], s[2:3], 9
	s_add_u32 s2, s2, s6
	s_addc_u32 s3, s3, s7
	s_lshl_b64 s[2:3], s[2:3], 2
	s_add_u32 s8, s76, s2
	s_addc_u32 s9, s77, s3
	s_add_u32 s10, s78, s2
	s_addc_u32 s11, s79, s3
	s_mov_b64 s[12:13], 0

; __device__ __forceinline__ void sa_rows(int kk, int b, const float* ck, const float* cv, const float* out, const float*& kr, const float*& vr, int& e) {
;     e = kk < 516 ? kk : 528 + 16 * ((kk - 516) >> 2) + ((kk - 516) & 3);
;     const int idx = 2051 - e;
;     if (idx >= WB) { kr = out + O_KS + (size_t)(b * 4 + idx - WB) * 512; vr = out + O_VS + (size_t)(b * 4 + idx - WB) * 512; }
;     else { kr = ck + ((size_t)b * WB + idx) * 512; vr = cv + ((size_t)b * WB + idx) * 512; }
; __device__ __forceinline__ void attn_sample_phase(const bf16* QKVb, const float* ck, const float* cv, const float* out, bf16* SPART, float2* SML, int gw, int NGW, int lane) {
;     ...
;         for (int g = 0; g < SA_KPC / 4; ++g) {
;             f32x4 kx[4][2], vx[4][2]; int ee[4];
; #pragma unroll
;             for (int t = 0; t < 4; ++t) {
;                 const float *kr, *vr; sa_rows(c * SA_KPC + g * 4 + t, b, ck, cv, out, kr, vr, ee[t]);
;                 kx[t][0] = __builtin_nontemporal_load((const f32x4*)(kr + 4 * lane)); kx[t][1] = __builtin_nontemporal_load((const f32x4*)(kr + 256 + 4 * lane));
;                 vx[t][0] = __builtin_nontemporal_load((const f32x4*)(vr + 4 * lane)); vx[t][1] = __builtin_nontemporal_load((const f32x4*)(vr + 256 + 4 * lane));
.Lsa0_1082:
	v_lshlrev_b32_e32 v3, 2, v102
	s_add_i32 m0, s29, 0x0
	s_nop 0
	global_load_lds_dwordx4 v3, s[8:9] nt
	global_load_lds_dwordx4 v3, s[8:9] offset:1024 nt
	s_add_i32 m0, s29, 0x800
	s_nop 0
	global_load_lds_dwordx4 v3, s[10:11] nt
	global_load_lds_dwordx4 v3, s[10:11] offset:1024 nt
	s_add_i32 s2, s26, 1
	s_add_i32 s3, s28, 0x211
	s_cmpk_lt_i32 s2, 0x204
	s_cselect_b32 s3, s2, s3
	s_cmp_lt_i32 s3, 4
	s_mov_b64 s[12:13], -1
	s_cbranch_scc1 .Lsa0_1084
	s_sub_i32 s8, 0x803, s3
	s_ashr_i32 s9, s8, 31
	s_lshl_b64 s[8:9], s[8:9], 9
	s_add_u32 s8, s8, s6
	s_addc_u32 s9, s9, s7
	s_lshl_b64 s[10:11], s[8:9], 2
	s_add_u32 s8, s76, s10
	s_addc_u32 s9, s77, s11
	s_add_u32 s10, s78, s10
	s_addc_u32 s11, s79, s11
	s_mov_b64 s[12:13], 0

; __device__ __forceinline__ void sa_rows(int kk, int b, const float* ck, const float* cv, const float* out, const float*& kr, const float*& vr, int& e) {
;     e = kk < 516 ? kk : 528 + 16 * ((kk - 516) >> 2) + ((kk - 516) & 3);
;     const int idx = 2051 - e;
;     if (idx >= WB) { kr = out + O_KS + (size_t)(b * 4 + idx - WB) * 512; vr = out + O_VS + (size_t)(b * 4 + idx - WB) * 512; }
;     else { kr = ck + ((size_t)b * WB + idx) * 512; vr = cv + ((size_t)b * WB + idx) * 512; }
; __device__ __forceinline__ void attn_sample_phase(const bf16* QKVb, const float* ck, const float* cv, const float* out, bf16* SPART, float2* SML, int gw, int NGW, int lane) {
;     ...
;         for (int g = 0; g < SA_KPC / 4; ++g) {
;             f32x4 kx[4][2], vx[4][2]; int ee[4];
; #pragma unroll
;             for (int t = 0; t < 4; ++t) {
;                 const float *kr, *vr; sa_rows(c * SA_KPC + g * 4 + t, b, ck, cv, out, kr, vr, ee[t]);
;                 kx[t][0] = __builtin_nontemporal_load((const f32x4*)(kr + 4 * lane)); kx[t][1] = __builtin_nontemporal_load((const f32x4*)(kr + 256 + 4 * lane));
;                 vx[t][0] = __builtin_nontemporal_load((const f32x4*)(vr + 4 * lane)); vx[t][1] = __builtin_nontemporal_load((const f32x4*)(vr + 256 + 4 * lane));
.Lsa0_1086:
	s_add_i32 m0, s29, 0x1000
	s_nop 0
	global_load_lds_dwordx4 v3, s[8:9] nt
	global_load_lds_dwordx4 v3, s[8:9] offset:1024 nt
	s_add_i32 m0, s29, 0x1800
	s_nop 0
	global_load_lds_dwordx4 v3, s[10:11] nt
	global_load_lds_dwordx4 v3, s[10:11] offset:1024 nt
	s_add_i32 s2, s26, 2
	s_add_i32 s8, s28, 0x212
	s_cmpk_lt_i32 s2, 0x204
	s_cselect_b32 s2, s2, s8
	s_cmp_lt_i32 s2, 4
	s_mov_b64 s[12:13], -1
	s_cbranch_scc1 .Lsa0_1088
	s_sub_i32 s8, 0x803, s2
	s_ashr_i32 s9, s8, 31
	s_lshl_b64 s[8:9], s[8:9], 9
	s_add_u32 s8, s8, s6
	s_addc_u32 s9, s9, s7
	s_lshl_b64 s[10:11], s[8:9], 2
	s_add_u32 s8, s76, s10
	s_addc_u32 s9, s77, s11
	s_add_u32 s10, s78, s10
	s_addc_u32 s11, s79, s11
	s_mov_b64 s[12:13], 0

; __device__ __forceinline__ void sa_rows(int kk, int b, const float* ck, const float* cv, const float* out, const float*& kr, const float*& vr, int& e) {
;     e = kk < 516 ? kk : 528 + 16 * ((kk - 516) >> 2) + ((kk - 516) & 3);
;     const int idx = 2051 - e;
;     if (idx >= WB) { kr = out + O_KS + (size_t)(b * 4 + idx - WB) * 512; vr = out + O_VS + (size_t)(b * 4 + idx - WB) * 512; }
;     else { kr = ck + ((size_t)b * WB + idx) * 512; vr = cv + ((size_t)b * WB + idx) * 512; }
; __device__ __forceinline__ void attn_sample_phase(const bf16* QKVb, const float* ck, const float* cv, const float* out, bf16* SPART, float2* SML, int gw, int NGW, int lane) {
;     ...
;         for (int g = 0; g < SA_KPC / 4; ++g) {
;             f32x4 kx[4][2], vx[4][2]; int ee[4];
; #pragma unroll
;             for (int t = 0; t < 4; ++t) {
;                 const float *kr, *vr; sa_rows(c * SA_KPC + g * 4 + t, b, ck, cv, out, kr, vr, ee[t]);
;                 kx[t][0] = __builtin_nontemporal_load((const f32x4*)(kr + 4 * lane)); kx[t][1] = __builtin_nontemporal_load((const f32x4*)(kr + 256 + 4 * lane));
;                 vx[t][0] = __builtin_nontemporal_load((const f32x4*)(vr + 4 * lane)); vx[t][1] = __builtin_nontemporal_load((const f32x4*)(vr + 256 + 4 * lane));
.Lsa0_1090:
	s_add_i32 m0, s29, 0x2000
	s_nop 0
	global_load_lds_dwordx4 v3, s[8:9] nt
	global_load_lds_dwordx4 v3, s[8:9] offset:1024 nt
	s_add_i32 m0, s29, 0x2800
	s_nop 0
	global_load_lds_dwordx4 v3, s[10:11] nt
	global_load_lds_dwordx4 v3, s[10:11] offset:1024 nt
	s_add_i32 s26, s26, 3
	s_addk_i32 s28, 0x213
	s_cmpk_lt_i32 s26, 0x204
	s_cselect_b32 s26, s26, s28
	s_cmp_lt_i32 s26, 4
	s_mov_b64 s[12:13], -1
	s_cbranch_scc1 .Lsa0_1092
	s_sub_i32 s8, 0x803, s26
	s_ashr_i32 s9, s8, 31
	s_lshl_b64 s[8:9], s[8:9], 9
	s_add_u32 s8, s8, s6
	s_addc_u32 s9, s9, s7
	s_lshl_b64 s[10:11], s[8:9], 2
	s_add_u32 s8, s76, s10
	s_addc_u32 s9, s77, s11
	s_add_u32 s10, s78, s10
	s_addc_u32 s11, s79, s11
	s_mov_b64 s[12:13], 0

; __device__ __forceinline__ float row16_sum(float v) { v += dppf<0xB1>(v); v += dppf<0x4E>(v); v += dppf<0x141>(v); v += dppf<0x128>(v); return v; }
; __device__ __forceinline__ void attn_sample_phase(const bf16* QKVb, const float* ck, const float* cv, const float* out, bf16* SPART, float2* SML, int gw, int NGW, int lane) {
;     ...
;         for (int g = 0; g < SA_KPC / 4; ++g) {
;             f32x4 kx[4][2], vx[4][2]; int ee[4];
; #pragma unroll
;             for (int t = 0; t < 4; ++t) {
;                 const float *kr, *vr; sa_rows(c * SA_KPC + g * 4 + t, b, ck, cv, out, kr, vr, ee[t]);
;                 kx[t][0] = __builtin_nontemporal_load((const f32x4*)(kr + 4 * lane)); kx[t][1] = __builtin_nontemporal_load((const f32x4*)(kr + 256 + 4 * lane));
;                 vx[t][0] = __builtin_nontemporal_load((const f32x4*)(vr + 4 * lane)); vx[t][1] = __builtin_nontemporal_load((const f32x4*)(vr + 256 + 4 * lane));
;             }
; #pragma unroll
;             for (int t = 0; t < 4; ++t)
; #pragma unroll
;                 for (int i = 0; i < 4; ++i) {
;                     const int dl = ee[t] - 3 + i;
;                     const int mult = dl >= 0 ? (int)(dl <= 128) + (int)(((dl & 3) == 0) && dl <= 512) + (int)(((dl & 15) == 0) && dl <= 2048) : 0;
;                     if (mult) {
;                         const float fm = (float)mult;
; #pragma unroll
;                         for (int u = 0; u < 2; ++u) {
;                             const f32x4 pr = q[i][u] * kx[t][u];
;                             const float s = row16_sum((pr[0] + pr[1]) + (pr[2] + pr[3]));
;                             const float mn = fmaxf(m[i][u], s), scl = __builtin_amdgcn_exp2f(m[i][u] - mn), p = fm * __builtin_amdgcn_exp2f(s - mn);
;                             m[i][u] = mn; l[i][u] = l[i][u] * scl + p; o[i][u] = o[i][u] * scl + vx[t][u] * p;
.Lsa0_1094:
	s_add_i32 m0, s29, 0x3000
	s_nop 0
	global_load_lds_dwordx4 v3, s[8:9] nt
	global_load_lds_dwordx4 v3, s[8:9] offset:1024 nt
	s_add_i32 m0, s29, 0x3800
	s_nop 0
	global_load_lds_dwordx4 v3, s[10:11] nt
	global_load_lds_dwordx4 v3, s[10:11] offset:1024 nt
	s_mov_b32 s98, s27
	s_mov_b32 s99, s3
	s_mov_b32 s100, s2
	s_mov_b32 s101, s26
	s_branch .LBB0_1078
.LBB0_1077:
	v_pk_mul_f32 v[50:51], v[50:51], v[146:147]
	v_pk_mul_f32 v[48:49], v[48:49], v[144:145]
	v_pk_mul_f32 v[42:43], v[42:43], v[150:151]
	v_pk_mov_b32 v[52:53], v[48:49], v[50:51] op_sel:[1,0]
	v_mov_b32_e32 v49, v51
	v_pk_add_f32 v[48:49], v[52:53], v[48:49]
	v_pk_mul_f32 v[40:41], v[40:41], v[148:149]
	v_add_f32_e32 v3, v48, v49
	v_max_f32_e32 v48, v97, v97
	s_nop 0
	v_add_f32_dpp v3, v3, v3 quad_perm:[1,0,3,2] row_mask:0xf bank_mask:0xf bound_ctrl:1
	s_nop 1
	v_add_f32_dpp v3, v3, v3 quad_perm:[2,3,0,1] row_mask:0xf bank_mask:0xf bound_ctrl:1
	s_nop 1
	v_add_f32_dpp v3, v3, v3 row_half_mirror row_mask:0xf bank_mask:0xf bound_ctrl:1
	s_nop 1
	v_add_f32_dpp v3, v3, v3 row_ror:8 row_mask:0xf bank_mask:0xf bound_ctrl:1
	v_max_f32_e32 v49, v48, v3
	v_sub_f32_e32 v3, v3, v49
	v_exp_f32_e32 v50, v3
	v_sub_f32_e32 v48, v97, v49
	v_exp_f32_e32 v52, v48
	v_mov_b32_e32 v157, v49
	v_mov_b32_e32 v48, v50
	v_pk_mul_f32 v[44:45], v[44:45], v[50:51] op_sel_hi:[1,0]
	v_pk_mul_f32 v[46:47], v[46:47], v[50:51] op_sel_hi:[1,0]
	v_pk_mov_b32 v[50:51], v[40:41], v[42:43] op_sel:[1,0]
	v_mov_b32_e32 v41, v43
	v_pk_add_f32 v[40:41], v[50:51], v[40:41]
	v_fmac_f32_e32 v48, v96, v52
	v_add_f32_e32 v3, v40, v41
	v_max_f32_e32 v40, v89, v89
	v_pk_fma_f32 v[10:11], v[10:11], v[52:53], v[46:47] op_sel_hi:[1,0,1]
	v_add_f32_dpp v3, v3, v3 quad_perm:[1,0,3,2] row_mask:0xf bank_mask:0xf bound_ctrl:1
	v_pk_fma_f32 v[8:9], v[8:9], v[52:53], v[44:45] op_sel_hi:[1,0,1]
	v_mov_b32_e32 v156, v48
	v_add_f32_dpp v3, v3, v3 quad_perm:[2,3,0,1] row_mask:0xf bank_mask:0xf bound_ctrl:1
	s_nop 1
	v_add_f32_dpp v3, v3, v3 row_half_mirror row_mask:0xf bank_mask:0xf bound_ctrl:1
	s_nop 1
	v_add_f32_dpp v3, v3, v3 row_ror:8 row_mask:0xf bank_mask:0xf bound_ctrl:1
	v_max_f32_e32 v41, v40, v3
	v_sub_f32_e32 v3, v3, v41
	v_sub_f32_e32 v40, v89, v41
	v_exp_f32_e32 v42, v3
	v_exp_f32_e32 v50, v40
	v_mov_b32_e32 v161, v41
	v_mov_b32_e32 v40, v42
	v_fmac_f32_e32 v40, v88, v50
	v_pk_mul_f32 v[36:37], v[36:37], v[42:43] op_sel_hi:[1,0]
	v_pk_mul_f32 v[38:39], v[38:39], v[42:43] op_sel_hi:[1,0]
	v_pk_fma_f32 v[4:5], v[4:5], v[50:51], v[36:37] op_sel_hi:[1,0,1]
	v_pk_fma_f32 v[6:7], v[6:7], v[50:51], v[38:39] op_sel_hi:[1,0,1]
	v_mov_b32_e32 v160, v40
	s_add_i32 s1, s1, 4
	s_add_i32 s25, s25, 16
	s_cmp_eq_u32 s1, 60
	s_cbranch_scc1 .LBB0_1134
.LBB0_1078:
	s_waitcnt vmcnt(0)
	ds_read_b128 v[96:99], v202 offset:0
	ds_read_b128 v[88:91], v202 offset:1024
	ds_read_b128 v[92:95], v202 offset:2048
	ds_read_b128 v[84:87], v202 offset:3072
	ds_read_b128 v[80:83], v202 offset:4096
	ds_read_b128 v[72:75], v202 offset:5120
	ds_read_b128 v[76:79], v202 offset:6144
	ds_read_b128 v[68:71], v202 offset:7168
	ds_read_b128 v[64:67], v202 offset:8192
	ds_read_b128 v[56:59], v202 offset:9216
	ds_read_b128 v[60:63], v202 offset:10240
	ds_read_b128 v[52:55], v202 offset:11264
	ds_read_b128 v[48:51], v202 offset:12288
	ds_read_b128 v[40:43], v202 offset:13312
	ds_read_b128 v[44:47], v202 offset:14336
	ds_read_b128 v[36:39], v202 offset:15360
	s_waitcnt lgkmcnt(0)
	s_cmp_eq_u32 s1, 56
	s_cbranch_scc1 .Lsa_nopf
	s_add_i32 s1, s1, 4
	s_add_i32 s25, s25, 16
	s_and_b32 s28, s25, 0x7ffffff0
	s_add_i32 s26, s24, s1
	s_add_i32 s2, s28, 0x210
	s_cmpk_lt_i32 s26, 0x204
	s_cselect_b32 s27, s26, s2
	s_cmp_gt_i32 s27, 3
	s_mov_b64 s[12:13], -1
	s_cbranch_scc0 .Lsa1_1080
	s_sub_i32 s2, 0x803, s27
	s_ashr_i32 s3, s2, 31
	s_lshl_b64 s[2:3], s[2:3], 9
	s_add_u32 s2, s2, s6
	s_addc_u32 s3, s3, s7
	s_lshl_b64 s[2:3], s[2:3], 2
	s_add_u32 s8, s76, s2
	s_addc_u32 s9, s77, s3
	s_add_u32 s10, s78, s2
	s_addc_u32 s11, s79, s3
	s_mov_b64 s[12:13], 0

; __device__ __forceinline__ float row16_sum(float v) { v += dppf<0xB1>(v); v += dppf<0x4E>(v); v += dppf<0x141>(v); v += dppf<0x128>(v); return v; }
; __device__ __forceinline__ void attn_sample_phase(const bf16* QKVb, const float* ck, const float* cv, const float* out, bf16* SPART, float2* SML, int gw, int NGW, int lane) {
;     ...
;         for (int g = 0; g < SA_KPC / 4; ++g) {
;             f32x4 kx[4][2], vx[4][2]; int ee[4];
; #pragma unroll
;             for (int t = 0; t < 4; ++t) {
;                 const float *kr, *vr; sa_rows(c * SA_KPC + g * 4 + t, b, ck, cv, out, kr, vr, ee[t]);
;                 kx[t][0] = __builtin_nontemporal_load((const f32x4*)(kr + 4 * lane)); kx[t][1] = __builtin_nontemporal_load((const f32x4*)(kr + 256 + 4 * lane));
;                 vx[t][0] = __builtin_nontemporal_load((const f32x4*)(vr + 4 * lane)); vx[t][1] = __builtin_nontemporal_load((const f32x4*)(vr + 256 + 4 * lane));
;             }
; #pragma unroll
;             for (int t = 0; t < 4; ++t)
; #pragma unroll
;                 for (int i = 0; i < 4; ++i) {
;                     const int dl = ee[t] - 3 + i;
;                     const int mult = dl >= 0 ? (int)(dl <= 128) + (int)(((dl & 3) == 0) && dl <= 512) + (int)(((dl & 15) == 0) && dl <= 2048) : 0;
;                     if (mult) {
;                         const float fm = (float)mult;
; #pragma unroll
;                         for (int u = 0; u < 2; ++u) {
;                             const f32x4 pr = q[i][u] * kx[t][u];
;                             const float s = row16_sum((pr[0] + pr[1]) + (pr[2] + pr[3]));
;                             const float mn = fmaxf(m[i][u], s), scl = __builtin_amdgcn_exp2f(m[i][u] - mn), p = fm * __builtin_amdgcn_exp2f(s - mn);
;                             m[i][u] = mn; l[i][u] = l[i][u] * scl + p; o[i][u] = o[i][u] * scl + vx[t][u] * p;
.Lsa1_1094:
	s_add_i32 m0, s29, 0x3000
	s_nop 0
	global_load_lds_dwordx4 v3, s[8:9] nt
	global_load_lds_dwordx4 v3, s[8:9] offset:1024 nt
	s_add_i32 m0, s29, 0x3800
	s_nop 0
	global_load_lds_dwordx4 v3, s[10:11] nt
	global_load_lds_dwordx4 v3, s[10:11] offset:1024 nt
	s_sub_i32 s1, s1, 4
	s_sub_i32 s25, s25, 16
	s_mov_b32 s28, s27
	s_mov_b32 s27, s98
	s_mov_b32 s98, s28
	s_mov_b32 s28, s3
	s_mov_b32 s3, s99
	s_mov_b32 s99, s28
	s_mov_b32 s28, s2
	s_mov_b32 s2, s100
	s_mov_b32 s100, s28
	s_mov_b32 s28, s26
	s_mov_b32 s26, s101
	s_mov_b32 s101, s28
	s_branch .Lsa_compute
.Lsa_nopf:
	s_mov_b32 s27, s98
	s_mov_b32 s3, s99
	s_mov_b32 s2, s100
	s_mov_b32 s26, s101
.Lsa_compute:
	s_add_i32 s8, s27, 0xffffff7c
	s_cmp_lt_u32 s8, 0xffffff7f
	s_cbranch_scc1 .LBB0_1100
	v_pk_mul_f32 v[174:175], v[98:99], v[110:111]
	v_pk_mul_f32 v[176:177], v[96:97], v[108:109]
	v_max_f32_e32 v103, v173, v173
	v_pk_mov_b32 v[178:179], v[176:177], v[174:175] op_sel:[1,0]
	v_mov_b32_e32 v177, v175
	v_pk_add_f32 v[174:175], v[178:179], v[176:177]
	v_pk_mul_f32 v[180:181], v[90:91], v[114:115]
	v_add_f32_e32 v3, v174, v175
	v_pk_mul_f32 v[182:183], v[88:89], v[112:113]
	s_nop 0
	v_add_f32_dpp v3, v3, v3 quad_perm:[1,0,3,2] row_mask:0xf bank_mask:0xf bound_ctrl:1
	v_pk_mov_b32 v[184:185], v[182:183], v[180:181] op_sel:[1,0]
	v_mov_b32_e32 v183, v181
	v_add_f32_dpp v3, v3, v3 quad_perm:[2,3,0,1] row_mask:0xf bank_mask:0xf bound_ctrl:1
	v_pk_add_f32 v[180:181], v[184:185], v[182:183]
	s_nop 0
	v_add_f32_dpp v3, v3, v3 row_half_mirror row_mask:0xf bank_mask:0xf bound_ctrl:1
	s_nop 1
	v_add_f32_dpp v3, v3, v3 row_ror:8 row_mask:0xf bank_mask:0xf bound_ctrl:1
	v_max_f32_e32 v175, v103, v3
	v_sub_f32_e32 v3, v3, v175
	v_exp_f32_e32 v176, v3
	v_add_f32_e32 v3, v180, v181
	v_sub_f32_e32 v103, v173, v175
	v_exp_f32_e32 v178, v103
	v_add_f32_dpp v3, v3, v3 quad_perm:[1,0,3,2] row_mask:0xf bank_mask:0xf bound_ctrl:1
	v_max_f32_e32 v103, v159, v159
	v_mov_b32_e32 v174, v176
	v_add_f32_dpp v3, v3, v3 quad_perm:[2,3,0,1] row_mask:0xf bank_mask:0xf bound_ctrl:1
	v_fmac_f32_e32 v174, v172, v178
	v_pk_mul_f32 v[172:173], v[92:93], v[176:177] op_sel_hi:[1,0]
	v_add_f32_dpp v3, v3, v3 row_half_mirror row_mask:0xf bank_mask:0xf bound_ctrl:1
	v_pk_mul_f32 v[176:177], v[94:95], v[176:177] op_sel_hi:[1,0]
	s_nop 0
	v_add_f32_dpp v3, v3, v3 row_ror:8 row_mask:0xf bank_mask:0xf bound_ctrl:1
	v_max_f32_e32 v179, v103, v3
	v_sub_f32_e32 v3, v3, v179
	v_sub_f32_e32 v103, v159, v179
	v_exp_f32_e32 v180, v3
	v_exp_f32_e32 v182, v103
	v_pk_fma_f32 v[34:35], v[34:35], v[178:179], v[176:177] op_sel_hi:[1,0,1]
	v_pk_fma_f32 v[32:33], v[32:33], v[178:179], v[172:173] op_sel_hi:[1,0,1]
	v_mov_b32_e32 v178, v180
	v_fmac_f32_e32 v178, v158, v182
	v_pk_mul_f32 v[158:159], v[84:85], v[180:181] op_sel_hi:[1,0]
	v_pk_mul_f32 v[172:173], v[86:87], v[180:181] op_sel_hi:[1,0]
	v_pk_fma_f32 v[28:29], v[28:29], v[182:183], v[158:159] op_sel_hi:[1,0,1]
	v_pk_fma_f32 v[30:31], v[30:31], v[182:183], v[172:173] op_sel_hi:[1,0,1]
	v_mov_b32_e32 v172, v174
	v_mov_b32_e32 v173, v175
	v_mov_b32_e32 v158, v178
	v_mov_b32_e32 v159, v179
	s_add_i32 s8, s27, 0xffffff7d
	s_cmp_lt_u32 s8, 0xffffff7f
	s_cbranch_scc0 .LBB0_1101

; __device__ __forceinline__ float row16_sum(float v) { v += dppf<0xB1>(v); v += dppf<0x4E>(v); v += dppf<0x141>(v); v += dppf<0x128>(v); return v; }
; __device__ __forceinline__ void attn_sample_phase(const bf16* QKVb, const float* ck, const float* cv, const float* out, bf16* SPART, float2* SML, int gw, int NGW, int lane) {
;     ...
; #pragma unroll
;             for (int t = 0; t < 4; ++t)
; #pragma unroll
;                 for (int i = 0; i < 4; ++i) {
;                     const int dl = ee[t] - 3 + i;
;                     const int mult = dl >= 0 ? (int)(dl <= 128) + (int)(((dl & 3) == 0) && dl <= 512) + (int)(((dl & 15) == 0) && dl <= 2048) : 0;
;                     if (mult) {
;                         const float fm = (float)mult;
; #pragma unroll
;                         for (int u = 0; u < 2; ++u) {
;                             const f32x4 pr = q[i][u] * kx[t][u];
;                             const float s = row16_sum((pr[0] + pr[1]) + (pr[2] + pr[3]));
;                             const float mn = fmaxf(m[i][u], s), scl = __builtin_amdgcn_exp2f(m[i][u] - mn), p = fm * __builtin_amdgcn_exp2f(s - mn);
;                             m[i][u] = mn; l[i][u] = l[i][u] * scl + p; o[i][u] = o[i][u] * scl + vx[t][u] * p;
;                         }
;                     }
;                 }
.LBB0_1099:
	v_mov_b32_e32 v96, v156
	v_mov_b32_e32 v97, v157
	v_mov_b32_e32 v88, v160
	v_mov_b32_e32 v89, v161
	s_add_i32 s8, s3, -3
	s_cmpk_gt_u32 s8, 0x80
	s_cbranch_scc0 .LBB0_1105
	s_branch .LBB0_1106

; __device__ __forceinline__ float row16_sum(float v) { v += dppf<0xB1>(v); v += dppf<0x4E>(v); v += dppf<0x141>(v); v += dppf<0x128>(v); return v; }
; __device__ __forceinline__ void attn_sample_phase(const bf16* QKVb, const float* ck, const float* cv, const float* out, bf16* SPART, float2* SML, int gw, int NGW, int lane) {
;     ...
; #pragma unroll
;             for (int t = 0; t < 4; ++t)
; #pragma unroll
;                 for (int i = 0; i < 4; ++i) {
;                     const int dl = ee[t] - 3 + i;
;                     const int mult = dl >= 0 ? (int)(dl <= 128) + (int)(((dl & 3) == 0) && dl <= 512) + (int)(((dl & 15) == 0) && dl <= 2048) : 0;
;                     if (mult) {
;                         const float fm = (float)mult;
; #pragma unroll
;                         for (int u = 0; u < 2; ++u) {
;                             const f32x4 pr = q[i][u] * kx[t][u];
;                             const float s = row16_sum((pr[0] + pr[1]) + (pr[2] + pr[3]));
;                             const float mn = fmaxf(m[i][u], s), scl = __builtin_amdgcn_exp2f(m[i][u] - mn), p = fm * __builtin_amdgcn_exp2f(s - mn);
;                             m[i][u] = mn; l[i][u] = l[i][u] * scl + p; o[i][u] = o[i][u] * scl + vx[t][u] * p;
;                         }
;                     }
;                 }
.LBB0_1101:
	v_pk_mul_f32 v[176:177], v[98:99], v[118:119]
	v_pk_mul_f32 v[180:181], v[96:97], v[116:117]
	v_max_f32_e32 v103, v171, v171
	v_pk_mov_b32 v[182:183], v[180:181], v[176:177] op_sel:[1,0]
	v_mov_b32_e32 v181, v177
	v_pk_add_f32 v[176:177], v[182:183], v[180:181]
	v_pk_mul_f32 v[184:185], v[90:91], v[122:123]
	v_add_f32_e32 v3, v176, v177
	v_pk_mul_f32 v[194:195], v[88:89], v[120:121]
	s_nop 0
	v_add_f32_dpp v3, v3, v3 quad_perm:[1,0,3,2] row_mask:0xf bank_mask:0xf bound_ctrl:1
	v_pk_mov_b32 v[196:197], v[194:195], v[184:185] op_sel:[1,0]
	v_mov_b32_e32 v195, v185
	v_add_f32_dpp v3, v3, v3 quad_perm:[2,3,0,1] row_mask:0xf bank_mask:0xf bound_ctrl:1
	v_pk_add_f32 v[184:185], v[196:197], v[194:195]
	s_nop 0
	v_add_f32_dpp v3, v3, v3 row_half_mirror row_mask:0xf bank_mask:0xf bound_ctrl:1
	s_nop 1
	v_add_f32_dpp v3, v3, v3 row_ror:8 row_mask:0xf bank_mask:0xf bound_ctrl:1
	v_max_f32_e32 v177, v103, v3
	v_sub_f32_e32 v3, v3, v177
	v_exp_f32_e32 v180, v3
	v_add_f32_e32 v3, v184, v185
	v_sub_f32_e32 v103, v171, v177
	v_exp_f32_e32 v182, v103
	v_add_f32_dpp v3, v3, v3 quad_perm:[1,0,3,2] row_mask:0xf bank_mask:0xf bound_ctrl:1
	v_max_f32_e32 v103, v155, v155
	v_mov_b32_e32 v176, v180
	v_add_f32_dpp v3, v3, v3 quad_perm:[2,3,0,1] row_mask:0xf bank_mask:0xf bound_ctrl:1
	v_fmac_f32_e32 v176, v170, v182
	v_pk_mul_f32 v[170:171], v[92:93], v[180:181] op_sel_hi:[1,0]
	v_add_f32_dpp v3, v3, v3 row_half_mirror row_mask:0xf bank_mask:0xf bound_ctrl:1
	v_pk_mul_f32 v[180:181], v[94:95], v[180:181] op_sel_hi:[1,0]
	s_nop 0
	v_add_f32_dpp v3, v3, v3 row_ror:8 row_mask:0xf bank_mask:0xf bound_ctrl:1
	v_max_f32_e32 v183, v103, v3
	v_sub_f32_e32 v3, v3, v183
	v_sub_f32_e32 v103, v155, v183
	v_exp_f32_e32 v184, v3
	v_exp_f32_e32 v194, v103
	v_pk_fma_f32 v[26:27], v[26:27], v[182:183], v[180:181] op_sel_hi:[1,0,1]
	v_pk_fma_f32 v[24:25], v[24:25], v[182:183], v[170:171] op_sel_hi:[1,0,1]
	v_mov_b32_e32 v182, v184
	v_fmac_f32_e32 v182, v154, v194
	v_pk_mul_f32 v[154:155], v[84:85], v[184:185] op_sel_hi:[1,0]
	v_pk_mul_f32 v[170:171], v[86:87], v[184:185] op_sel_hi:[1,0]
	v_pk_fma_f32 v[20:21], v[20:21], v[194:195], v[154:155] op_sel_hi:[1,0,1]
	v_pk_fma_f32 v[22:23], v[22:23], v[194:195], v[170:171] op_sel_hi:[1,0,1]
	v_mov_b32_e32 v170, v176
	v_mov_b32_e32 v171, v177
	v_mov_b32_e32 v154, v182
	v_mov_b32_e32 v155, v183
	s_add_i32 s8, s27, 0xffffff7e
	s_cmp_lt_u32 s8, 0xffffff7f
	s_cbranch_scc1 .LBB0_1097
.LBB0_1102:
	v_pk_mul_f32 v[180:181], v[98:99], v[126:127]
	v_pk_mul_f32 v[184:185], v[96:97], v[124:125]
	v_max_f32_e32 v103, v169, v169
	v_pk_mov_b32 v[194:195], v[184:185], v[180:181] op_sel:[1,0]
	v_mov_b32_e32 v185, v181
	v_pk_add_f32 v[180:181], v[194:195], v[184:185]
	v_pk_mul_f32 v[198:199], v[88:89], v[128:129]
	v_add_f32_e32 v3, v180, v181
	s_nop 1
	v_add_f32_dpp v3, v3, v3 quad_perm:[1,0,3,2] row_mask:0xf bank_mask:0xf bound_ctrl:1
	s_nop 1
	v_add_f32_dpp v3, v3, v3 quad_perm:[2,3,0,1] row_mask:0xf bank_mask:0xf bound_ctrl:1
	s_nop 1
	v_add_f32_dpp v3, v3, v3 row_half_mirror row_mask:0xf bank_mask:0xf bound_ctrl:1
	s_nop 1
	v_add_f32_dpp v3, v3, v3 row_ror:8 row_mask:0xf bank_mask:0xf bound_ctrl:1
	v_max_f32_e32 v181, v103, v3
	v_sub_f32_e32 v3, v3, v181
	v_sub_f32_e32 v103, v169, v181
	v_exp_f32_e32 v184, v3
	v_exp_f32_e32 v194, v103
	v_max_f32_e32 v103, v153, v153
	v_mov_b32_e32 v180, v184
	v_fmac_f32_e32 v180, v168, v194
	v_pk_mul_f32 v[168:169], v[92:93], v[184:185] op_sel_hi:[1,0]
	v_pk_mul_f32 v[196:197], v[94:95], v[184:185] op_sel_hi:[1,0]
	v_pk_mul_f32 v[184:185], v[90:91], v[142:143]
	v_pk_fma_f32 v[16:17], v[16:17], v[194:195], v[168:169] op_sel_hi:[1,0,1]
	v_pk_mov_b32 v[200:201], v[198:199], v[184:185] op_sel:[1,0]
	v_mov_b32_e32 v199, v185
	v_pk_add_f32 v[184:185], v[200:201], v[198:199]
	v_pk_fma_f32 v[18:19], v[18:19], v[194:195], v[196:197] op_sel_hi:[1,0,1]
	v_add_f32_e32 v3, v184, v185
	s_nop 1
	v_add_f32_dpp v3, v3, v3 quad_perm:[1,0,3,2] row_mask:0xf bank_mask:0xf bound_ctrl:1
	s_nop 1
	v_add_f32_dpp v3, v3, v3 quad_perm:[2,3,0,1] row_mask:0xf bank_mask:0xf bound_ctrl:1
	s_nop 1
	v_add_f32_dpp v3, v3, v3 row_half_mirror row_mask:0xf bank_mask:0xf bound_ctrl:1
	s_nop 1
	v_add_f32_dpp v3, v3, v3 row_ror:8 row_mask:0xf bank_mask:0xf bound_ctrl:1
	v_max_f32_e32 v185, v103, v3
	v_sub_f32_e32 v3, v3, v185
	v_sub_f32_e32 v103, v153, v185
	v_exp_f32_e32 v198, v3
	v_exp_f32_e32 v200, v103
	v_mov_b32_e32 v184, v198
	v_fmac_f32_e32 v184, v152, v200
	v_pk_mul_f32 v[152:153], v[84:85], v[198:199] op_sel_hi:[1,0]
	v_pk_mul_f32 v[168:169], v[86:87], v[198:199] op_sel_hi:[1,0]
	v_pk_fma_f32 v[12:13], v[12:13], v[200:201], v[152:153] op_sel_hi:[1,0,1]
	v_pk_fma_f32 v[14:15], v[14:15], v[200:201], v[168:169] op_sel_hi:[1,0,1]
	v_mov_b32_e32 v168, v180
	v_mov_b32_e32 v169, v181
	v_mov_b32_e32 v152, v184
	v_mov_b32_e32 v153, v185
	s_cmp_lt_i32 s27, 0
	s_cbranch_scc1 .LBB0_1098

; __device__ __forceinline__ float row16_sum(float v) { v += dppf<0xB1>(v); v += dppf<0x4E>(v); v += dppf<0x141>(v); v += dppf<0x128>(v); return v; }
; __device__ __forceinline__ void attn_sample_phase(const bf16* QKVb, const float* ck, const float* cv, const float* out, bf16* SPART, float2* SML, int gw, int NGW, int lane) {
;     ...
; #pragma unroll
;             for (int t = 0; t < 4; ++t)
; #pragma unroll
;                 for (int i = 0; i < 4; ++i) {
;                     const int dl = ee[t] - 3 + i;
;                     const int mult = dl >= 0 ? (int)(dl <= 128) + (int)(((dl & 3) == 0) && dl <= 512) + (int)(((dl & 15) == 0) && dl <= 2048) : 0;
;                     if (mult) {
;                         const float fm = (float)mult;
; #pragma unroll
;                         for (int u = 0; u < 2; ++u) {
;                             const f32x4 pr = q[i][u] * kx[t][u];
;                             const float s = row16_sum((pr[0] + pr[1]) + (pr[2] + pr[3]));
;                             const float mn = fmaxf(m[i][u], s), scl = __builtin_amdgcn_exp2f(m[i][u] - mn), p = fm * __builtin_amdgcn_exp2f(s - mn);
;                             m[i][u] = mn; l[i][u] = l[i][u] * scl + p; o[i][u] = o[i][u] * scl + vx[t][u] * p;
;                         }
;                     }
;                 }
.LBB0_1104:
	v_pk_mul_f32 v[98:99], v[98:99], v[146:147]
	v_pk_mul_f32 v[96:97], v[96:97], v[144:145]
	v_pk_mul_f32 v[90:91], v[90:91], v[150:151]
	v_pk_mov_b32 v[194:195], v[96:97], v[98:99] op_sel:[1,0]
	v_mov_b32_e32 v97, v99
	v_pk_add_f32 v[96:97], v[194:195], v[96:97]
	v_cvt_f32_ubyte0_e32 v99, v3
	v_add_f32_e32 v96, v96, v97
	v_max_f32_e32 v97, v157, v157
	v_pk_mul_f32 v[88:89], v[88:89], v[148:149]
	v_add_f32_dpp v96, v96, v96 quad_perm:[1,0,3,2] row_mask:0xf bank_mask:0xf bound_ctrl:1
	s_nop 1
	v_add_f32_dpp v96, v96, v96 quad_perm:[2,3,0,1] row_mask:0xf bank_mask:0xf bound_ctrl:1
	s_nop 1
	v_add_f32_dpp v96, v96, v96 row_half_mirror row_mask:0xf bank_mask:0xf bound_ctrl:1
	s_nop 1
	v_add_f32_dpp v96, v96, v96 row_ror:8 row_mask:0xf bank_mask:0xf bound_ctrl:1
	v_max_f32_e32 v97, v97, v96
	v_sub_f32_e32 v98, v157, v97
	v_sub_f32_e32 v96, v96, v97
	v_exp_f32_e32 v98, v98
	v_exp_f32_e32 v157, v96
	s_nop 0
	v_pk_mul_f32 v[156:157], v[156:157], v[98:99]
	v_pk_mul_f32 v[92:93], v[92:93], v[156:157] op_sel:[0,1]
	v_pk_mul_f32 v[94:95], v[94:95], v[156:157] op_sel:[0,1]
	v_pk_fma_f32 v[8:9], v[8:9], v[98:99], v[92:93] op_sel_hi:[1,0,1]
	v_pk_mov_b32 v[92:93], v[88:89], v[90:91] op_sel:[1,0]
	v_mov_b32_e32 v89, v91
	v_pk_add_f32 v[88:89], v[92:93], v[88:89]
	v_pk_fma_f32 v[10:11], v[10:11], v[98:99], v[94:95] op_sel_hi:[1,0,1]
	v_add_f32_e32 v3, v88, v89
	v_max_f32_e32 v88, v161, v161
	v_add_f32_e32 v96, v156, v157
	v_add_f32_dpp v3, v3, v3 quad_perm:[1,0,3,2] row_mask:0xf bank_mask:0xf bound_ctrl:1
	v_mov_b64_e32 v[156:157], v[96:97]
	s_nop 0
	v_add_f32_dpp v3, v3, v3 quad_perm:[2,3,0,1] row_mask:0xf bank_mask:0xf bound_ctrl:1
	s_nop 1
	v_add_f32_dpp v3, v3, v3 row_half_mirror row_mask:0xf bank_mask:0xf bound_ctrl:1
	s_nop 1
	v_add_f32_dpp v3, v3, v3 row_ror:8 row_mask:0xf bank_mask:0xf bound_ctrl:1
	v_max_f32_e32 v89, v88, v3
	v_sub_f32_e32 v88, v161, v89
	v_sub_f32_e32 v3, v3, v89
	v_exp_f32_e32 v98, v88
	v_exp_f32_e32 v161, v3
	s_nop 0
	v_pk_mul_f32 v[90:91], v[160:161], v[98:99]
	v_pk_mul_f32 v[84:85], v[84:85], v[90:91] op_sel:[0,1]
	v_pk_mul_f32 v[86:87], v[86:87], v[90:91] op_sel:[0,1]
	v_add_f32_e32 v88, v90, v91
	v_pk_fma_f32 v[6:7], v[6:7], v[98:99], v[86:87] op_sel_hi:[1,0,1]
	v_pk_fma_f32 v[4:5], v[4:5], v[98:99], v[84:85] op_sel_hi:[1,0,1]
	v_mov_b64_e32 v[160:161], v[88:89]
	s_add_i32 s8, s3, -3
	s_cmpk_gt_u32 s8, 0x80
	s_cbranch_scc1 .LBB0_1106
.LBB0_1105:
	v_pk_mul_f32 v[84:85], v[82:83], v[110:111]
	v_pk_mul_f32 v[86:87], v[80:81], v[108:109]
	v_pk_mul_f32 v[92:93], v[74:75], v[114:115]
	v_pk_mov_b32 v[90:91], v[86:87], v[84:85] op_sel:[1,0]
	v_mov_b32_e32 v87, v85
	v_pk_add_f32 v[84:85], v[90:91], v[86:87]
	v_pk_mul_f32 v[94:95], v[72:73], v[112:113]
	v_add_f32_e32 v3, v84, v85
	v_max_f32_e32 v84, v173, v173
	v_pk_mov_b32 v[98:99], v[94:95], v[92:93] op_sel:[1,0]
	v_add_f32_dpp v3, v3, v3 quad_perm:[1,0,3,2] row_mask:0xf bank_mask:0xf bound_ctrl:1
	v_mov_b32_e32 v95, v93
	v_pk_add_f32 v[92:93], v[98:99], v[94:95]
	v_add_f32_dpp v3, v3, v3 quad_perm:[2,3,0,1] row_mask:0xf bank_mask:0xf bound_ctrl:1
	v_max_f32_e32 v87, v159, v159
	s_nop 0
	v_add_f32_dpp v3, v3, v3 row_half_mirror row_mask:0xf bank_mask:0xf bound_ctrl:1
	s_nop 1
	v_add_f32_dpp v3, v3, v3 row_ror:8 row_mask:0xf bank_mask:0xf bound_ctrl:1
	v_max_f32_e32 v175, v84, v3
	v_sub_f32_e32 v3, v3, v175
	v_exp_f32_e32 v84, v3
	v_add_f32_e32 v3, v92, v93
	v_sub_f32_e32 v85, v173, v175
	v_exp_f32_e32 v86, v85
	v_add_f32_dpp v3, v3, v3 quad_perm:[1,0,3,2] row_mask:0xf bank_mask:0xf bound_ctrl:1
	v_mov_b32_e32 v174, v84
	v_pk_mul_f32 v[90:91], v[76:77], v[84:85] op_sel_hi:[1,0]
	v_add_f32_dpp v3, v3, v3 quad_perm:[2,3,0,1] row_mask:0xf bank_mask:0xf bound_ctrl:1
	v_pk_mul_f32 v[84:85], v[78:79], v[84:85] op_sel_hi:[1,0]
	v_fmac_f32_e32 v174, v172, v86
	v_add_f32_dpp v3, v3, v3 row_half_mirror row_mask:0xf bank_mask:0xf bound_ctrl:1
	v_mov_b32_e32 v172, v174
	v_mov_b32_e32 v173, v175
	v_add_f32_dpp v3, v3, v3 row_ror:8 row_mask:0xf bank_mask:0xf bound_ctrl:1
	v_max_f32_e32 v179, v87, v3
	v_sub_f32_e32 v3, v3, v179
	v_sub_f32_e32 v87, v159, v179
	v_exp_f32_e32 v92, v3
	v_exp_f32_e32 v94, v87
	v_pk_fma_f32 v[34:35], v[34:35], v[86:87], v[84:85] op_sel_hi:[1,0,1]
	v_pk_fma_f32 v[32:33], v[32:33], v[86:87], v[90:91] op_sel_hi:[1,0,1]
	v_mov_b32_e32 v178, v92
	v_fmac_f32_e32 v178, v158, v94
	v_pk_mul_f32 v[84:85], v[68:69], v[92:93] op_sel_hi:[1,0]
	v_pk_mul_f32 v[86:87], v[70:71], v[92:93] op_sel_hi:[1,0]
	v_pk_fma_f32 v[28:29], v[28:29], v[94:95], v[84:85] op_sel_hi:[1,0,1]
	v_pk_fma_f32 v[30:31], v[30:31], v[94:95], v[86:87] op_sel_hi:[1,0,1]
	v_mov_b32_e32 v158, v178
	v_mov_b32_e32 v159, v179
.LBB0_1106:
	s_add_i32 s8, s3, -2
	s_cmpk_gt_u32 s8, 0x80
	s_cbranch_scc1 .LBB0_1109
	v_pk_mul_f32 v[84:85], v[82:83], v[118:119]
	v_pk_mul_f32 v[86:87], v[80:81], v[116:117]
	v_pk_mul_f32 v[92:93], v[74:75], v[122:123]
	v_pk_mov_b32 v[90:91], v[86:87], v[84:85] op_sel:[1,0]
	v_mov_b32_e32 v87, v85
	v_pk_add_f32 v[84:85], v[90:91], v[86:87]
	v_pk_mul_f32 v[94:95], v[72:73], v[120:121]
	v_add_f32_e32 v3, v84, v85
	v_max_f32_e32 v84, v171, v171
	v_pk_mov_b32 v[98:99], v[94:95], v[92:93] op_sel:[1,0]
	v_add_f32_dpp v3, v3, v3 quad_perm:[1,0,3,2] row_mask:0xf bank_mask:0xf bound_ctrl:1
	v_mov_b32_e32 v95, v93
	v_pk_add_f32 v[92:93], v[98:99], v[94:95]
	v_add_f32_dpp v3, v3, v3 quad_perm:[2,3,0,1] row_mask:0xf bank_mask:0xf bound_ctrl:1
	v_max_f32_e32 v87, v155, v155
	s_nop 0
	v_add_f32_dpp v3, v3, v3 row_half_mirror row_mask:0xf bank_mask:0xf bound_ctrl:1
	s_nop 1
	v_add_f32_dpp v3, v3, v3 row_ror:8 row_mask:0xf bank_mask:0xf bound_ctrl:1
	v_max_f32_e32 v177, v84, v3
	v_sub_f32_e32 v3, v3, v177
	v_exp_f32_e32 v84, v3
	v_add_f32_e32 v3, v92, v93
	v_sub_f32_e32 v85, v171, v177
	v_exp_f32_e32 v86, v85
	v_add_f32_dpp v3, v3, v3 quad_perm:[1,0,3,2] row_mask:0xf bank_mask:0xf bound_ctrl:1
	v_mov_b32_e32 v176, v84
	v_pk_mul_f32 v[90:91], v[76:77], v[84:85] op_sel_hi:[1,0]
	v_add_f32_dpp v3, v3, v3 quad_perm:[2,3,0,1] row_mask:0xf bank_mask:0xf bound_ctrl:1
	v_pk_mul_f32 v[84:85], v[78:79], v[84:85] op_sel_hi:[1,0]
	v_fmac_f32_e32 v176, v170, v86
	v_add_f32_dpp v3, v3, v3 row_half_mirror row_mask:0xf bank_mask:0xf bound_ctrl:1
	v_mov_b32_e32 v170, v176
	v_mov_b32_e32 v171, v177
	v_add_f32_dpp v3, v3, v3 row_ror:8 row_mask:0xf bank_mask:0xf bound_ctrl:1
	v_max_f32_e32 v183, v87, v3
	v_sub_f32_e32 v3, v3, v183
	v_sub_f32_e32 v87, v155, v183
	v_exp_f32_e32 v92, v3
	v_exp_f32_e32 v94, v87
	v_pk_fma_f32 v[26:27], v[26:27], v[86:87], v[84:85] op_sel_hi:[1,0,1]
	v_pk_fma_f32 v[24:25], v[24:25], v[86:87], v[90:91] op_sel_hi:[1,0,1]
	v_mov_b32_e32 v182, v92
	v_fmac_f32_e32 v182, v154, v94
	v_pk_mul_f32 v[84:85], v[68:69], v[92:93] op_sel_hi:[1,0]
	v_pk_mul_f32 v[86:87], v[70:71], v[92:93] op_sel_hi:[1,0]
	v_pk_fma_f32 v[20:21], v[20:21], v[94:95], v[84:85] op_sel_hi:[1,0,1]
	v_pk_fma_f32 v[22:23], v[22:23], v[94:95], v[86:87] op_sel_hi:[1,0,1]
	v_mov_b32_e32 v154, v182
	v_mov_b32_e32 v155, v183
	s_cmp_lt_i32 s3, 1
	s_cbranch_scc0 .LBB0_1110

; __device__ __forceinline__ float row16_sum(float v) { v += dppf<0xB1>(v); v += dppf<0x4E>(v); v += dppf<0x141>(v); v += dppf<0x128>(v); return v; }
; __device__ __forceinline__ void attn_sample_phase(const bf16* QKVb, const float* ck, const float* cv, const float* out, bf16* SPART, float2* SML, int gw, int NGW, int lane) {
;     ...
; #pragma unroll
;             for (int t = 0; t < 4; ++t)
; #pragma unroll
;                 for (int i = 0; i < 4; ++i) {
;                     const int dl = ee[t] - 3 + i;
;                     const int mult = dl >= 0 ? (int)(dl <= 128) + (int)(((dl & 3) == 0) && dl <= 512) + (int)(((dl & 15) == 0) && dl <= 2048) : 0;
;                     if (mult) {
;                         const float fm = (float)mult;
; #pragma unroll
;                         for (int u = 0; u < 2; ++u) {
;                             const f32x4 pr = q[i][u] * kx[t][u];
;                             const float s = row16_sum((pr[0] + pr[1]) + (pr[2] + pr[3]));
;                             const float mn = fmaxf(m[i][u], s), scl = __builtin_amdgcn_exp2f(m[i][u] - mn), p = fm * __builtin_amdgcn_exp2f(s - mn);
;                             m[i][u] = mn; l[i][u] = l[i][u] * scl + p; o[i][u] = o[i][u] * scl + vx[t][u] * p;
;                         }
;                     }
;                 }
.LBB0_1110:
	s_add_i32 s10, s3, -1
	s_cmpk_lt_u32 s3, 0x82
	s_cselect_b64 s[8:9], -1, 0
	s_cmpk_lt_u32 s3, 0x202
	v_cndmask_b32_e64 v3, 0, 1, s[8:9]
	s_cselect_b64 s[8:9], -1, 0
	v_cndmask_b32_e64 v84, 0, 1, s[8:9]
	s_and_b32 s8, s10, 12
	s_cmp_eq_u32 s8, 0
	s_cselect_b64 s[8:9], -1, 0
	s_cmpk_lt_u32 s3, 0x802
	s_cselect_b64 s[10:11], -1, 0
	s_and_b64 vcc, s[10:11], s[8:9]
	v_addc_co_u32_e32 v3, vcc, v84, v3, vcc
	v_cmp_eq_u32_e32 vcc, 0, v3
	s_cbranch_vccnz .LBB0_1112
.LBB0_1111:
	v_pk_mul_f32 v[84:85], v[82:83], v[126:127]
	v_pk_mul_f32 v[86:87], v[80:81], v[124:125]
	s_nop 0
	v_pk_mov_b32 v[90:91], v[86:87], v[84:85] op_sel:[1,0]
	v_mov_b32_e32 v87, v85
	v_pk_add_f32 v[84:85], v[90:91], v[86:87]
	v_cvt_f32_ubyte0_e32 v87, v3
	v_add_f32_e32 v84, v84, v85
	v_max_f32_e32 v85, v169, v169
	s_nop 0
	v_add_f32_dpp v84, v84, v84 quad_perm:[1,0,3,2] row_mask:0xf bank_mask:0xf bound_ctrl:1
	s_nop 1
	v_add_f32_dpp v84, v84, v84 quad_perm:[2,3,0,1] row_mask:0xf bank_mask:0xf bound_ctrl:1
	s_nop 1
	v_add_f32_dpp v84, v84, v84 row_half_mirror row_mask:0xf bank_mask:0xf bound_ctrl:1
	s_nop 1
	v_add_f32_dpp v84, v84, v84 row_ror:8 row_mask:0xf bank_mask:0xf bound_ctrl:1
	v_max_f32_e32 v85, v85, v84
	v_sub_f32_e32 v86, v169, v85
	v_sub_f32_e32 v84, v84, v85
	v_exp_f32_e32 v86, v86
	v_exp_f32_e32 v181, v84
	v_max_f32_e32 v84, v153, v153
	v_mov_b32_e32 v169, v85
	v_pk_mul_f32 v[90:91], v[180:181], v[86:87]
	v_pk_mul_f32 v[92:93], v[76:77], v[90:91] op_sel:[0,1]
	v_pk_mul_f32 v[94:95], v[78:79], v[90:91] op_sel:[0,1]
	v_pk_fma_f32 v[16:17], v[16:17], v[86:87], v[92:93] op_sel_hi:[1,0,1]
	v_pk_fma_f32 v[18:19], v[18:19], v[86:87], v[94:95] op_sel_hi:[1,0,1]
	v_pk_mul_f32 v[92:93], v[74:75], v[142:143]
	v_pk_mul_f32 v[94:95], v[72:73], v[128:129]
	s_nop 0
	v_pk_mov_b32 v[98:99], v[94:95], v[92:93] op_sel:[1,0]
	v_mov_b32_e32 v95, v93
	v_pk_add_f32 v[92:93], v[98:99], v[94:95]
	s_nop 0
	v_add_f32_e32 v3, v92, v93
	s_nop 1
	v_add_f32_dpp v3, v3, v3 quad_perm:[1,0,3,2] row_mask:0xf bank_mask:0xf bound_ctrl:1
	s_nop 1
	v_add_f32_dpp v3, v3, v3 quad_perm:[2,3,0,1] row_mask:0xf bank_mask:0xf bound_ctrl:1
	s_nop 1
	v_add_f32_dpp v3, v3, v3 row_half_mirror row_mask:0xf bank_mask:0xf bound_ctrl:1
	s_nop 1
	v_add_f32_dpp v3, v3, v3 row_ror:8 row_mask:0xf bank_mask:0xf bound_ctrl:1
	v_max_f32_e32 v93, v84, v3
	v_sub_f32_e32 v84, v153, v93
	v_sub_f32_e32 v3, v3, v93
	v_exp_f32_e32 v86, v84
	v_exp_f32_e32 v185, v3
	v_add_f32_e32 v84, v90, v91
	v_mov_b64_e32 v[180:181], v[84:85]
	v_mov_b32_e32 v168, v84
	v_pk_mul_f32 v[94:95], v[184:185], v[86:87]
	v_pk_mul_f32 v[98:99], v[68:69], v[94:95] op_sel:[0,1]
	v_pk_mul_f32 v[152:153], v[70:71], v[94:95] op_sel:[0,1]
	v_add_f32_e32 v92, v94, v95
	v_pk_fma_f32 v[14:15], v[14:15], v[86:87], v[152:153] op_sel_hi:[1,0,1]
	v_pk_fma_f32 v[12:13], v[12:13], v[86:87], v[98:99] op_sel_hi:[1,0,1]
	v_mov_b64_e32 v[184:185], v[92:93]
	v_mov_b32_e32 v152, v92
	v_mov_b32_e32 v153, v93
.LBB0_1112:
	s_cmpk_gt_u32 s3, 0x80
	s_cbranch_scc1 .LBB0_1116
	v_pk_mul_f32 v[82:83], v[82:83], v[146:147]
	v_pk_mul_f32 v[80:81], v[80:81], v[144:145]
	v_pk_mul_f32 v[74:75], v[74:75], v[150:151]
	v_pk_mov_b32 v[84:85], v[80:81], v[82:83] op_sel:[1,0]
	v_mov_b32_e32 v81, v83
	v_pk_add_f32 v[80:81], v[84:85], v[80:81]
	v_pk_mul_f32 v[72:73], v[72:73], v[148:149]
	v_add_f32_e32 v3, v80, v81
	v_max_f32_e32 v80, v97, v97
	s_nop 0
	v_add_f32_dpp v3, v3, v3 quad_perm:[1,0,3,2] row_mask:0xf bank_mask:0xf bound_ctrl:1
	s_nop 1
	v_add_f32_dpp v3, v3, v3 quad_perm:[2,3,0,1] row_mask:0xf bank_mask:0xf bound_ctrl:1
	s_nop 1
	v_add_f32_dpp v3, v3, v3 row_half_mirror row_mask:0xf bank_mask:0xf bound_ctrl:1
	s_nop 1
	v_add_f32_dpp v3, v3, v3 row_ror:8 row_mask:0xf bank_mask:0xf bound_ctrl:1
	v_max_f32_e32 v157, v80, v3
	v_sub_f32_e32 v3, v3, v157
	v_exp_f32_e32 v80, v3
	v_sub_f32_e32 v81, v97, v157
	v_exp_f32_e32 v82, v81
	v_mov_b32_e32 v97, v157
	v_mov_b32_e32 v156, v80
	v_pk_mul_f32 v[76:77], v[76:77], v[80:81] op_sel_hi:[1,0]
	v_pk_mul_f32 v[78:79], v[78:79], v[80:81] op_sel_hi:[1,0]
	v_pk_mov_b32 v[80:81], v[72:73], v[74:75] op_sel:[1,0]
	v_mov_b32_e32 v73, v75
	v_pk_add_f32 v[72:73], v[80:81], v[72:73]
	v_fmac_f32_e32 v156, v96, v82
	v_add_f32_e32 v3, v72, v73
	v_max_f32_e32 v72, v89, v89
	v_pk_fma_f32 v[10:11], v[10:11], v[82:83], v[78:79] op_sel_hi:[1,0,1]
	v_add_f32_dpp v3, v3, v3 quad_perm:[1,0,3,2] row_mask:0xf bank_mask:0xf bound_ctrl:1
	v_pk_fma_f32 v[8:9], v[8:9], v[82:83], v[76:77] op_sel_hi:[1,0,1]
	v_mov_b32_e32 v96, v156
	v_add_f32_dpp v3, v3, v3 quad_perm:[2,3,0,1] row_mask:0xf bank_mask:0xf bound_ctrl:1
	s_nop 1
	v_add_f32_dpp v3, v3, v3 row_half_mirror row_mask:0xf bank_mask:0xf bound_ctrl:1
	s_nop 1
	v_add_f32_dpp v3, v3, v3 row_ror:8 row_mask:0xf bank_mask:0xf bound_ctrl:1
	v_max_f32_e32 v161, v72, v3
	v_sub_f32_e32 v3, v3, v161
	v_sub_f32_e32 v73, v89, v161
	v_exp_f32_e32 v72, v3
	v_exp_f32_e32 v74, v73
	v_mov_b32_e32 v89, v161
	v_mov_b32_e32 v160, v72
	v_fmac_f32_e32 v160, v88, v74
	v_pk_mul_f32 v[68:69], v[68:69], v[72:73] op_sel_hi:[1,0]
	v_pk_mul_f32 v[70:71], v[70:71], v[72:73] op_sel_hi:[1,0]
	v_pk_fma_f32 v[4:5], v[4:5], v[74:75], v[68:69] op_sel_hi:[1,0,1]
	v_pk_fma_f32 v[6:7], v[6:7], v[74:75], v[70:71] op_sel_hi:[1,0,1]
	v_mov_b32_e32 v88, v160
	s_add_i32 s3, s2, -3
	s_cmpk_gt_u32 s3, 0x80
	s_cbranch_scc0 .LBB0_1117

; __device__ __forceinline__ void attn_sample_phase(const bf16* QKVb, const float* ck, const float* cv, const float* out, bf16* SPART, float2* SML, int gw, int NGW, int lane) {
;     ...
;                     const int dl = ee[t] - 3 + i;
;                     const int mult = dl >= 0 ? (int)(dl <= 128) + (int)(((dl & 3) == 0) && dl <= 512) + (int)(((dl & 15) == 0) && dl <= 2048) : 0;
.LBB0_1115:
	s_add_i32 s3, s2, -2
	s_cmpk_lt_u32 s3, 0x81
	s_cselect_b64 s[8:9], -1, 0
	s_cmpk_lt_u32 s3, 0x201
	v_cndmask_b32_e64 v3, 0, 1, s[8:9]
	s_cselect_b64 s[8:9], -1, 0
	v_cndmask_b32_e64 v68, 0, 1, s[8:9]
	s_and_b32 s8, s3, 12
	s_cmp_eq_u32 s8, 0
	s_cselect_b64 s[8:9], -1, 0
	s_cmpk_lt_u32 s3, 0x801
	s_cselect_b64 s[10:11], -1, 0
	s_and_b64 vcc, s[10:11], s[8:9]
	v_addc_co_u32_e32 v3, vcc, v68, v3, vcc
	v_cmp_eq_u32_e32 vcc, 0, v3
	s_cbranch_vccz .LBB0_1119
	s_branch .LBB0_1120

; __device__ __forceinline__ float row16_sum(float v) { v += dppf<0xB1>(v); v += dppf<0x4E>(v); v += dppf<0x141>(v); v += dppf<0x128>(v); return v; }
; __device__ __forceinline__ void attn_sample_phase(const bf16* QKVb, const float* ck, const float* cv, const float* out, bf16* SPART, float2* SML, int gw, int NGW, int lane) {
;     ...
; #pragma unroll
;             for (int t = 0; t < 4; ++t)
; #pragma unroll
;                 for (int i = 0; i < 4; ++i) {
;                     const int dl = ee[t] - 3 + i;
;                     const int mult = dl >= 0 ? (int)(dl <= 128) + (int)(((dl & 3) == 0) && dl <= 512) + (int)(((dl & 15) == 0) && dl <= 2048) : 0;
;                     if (mult) {
;                         const float fm = (float)mult;
; #pragma unroll
;                         for (int u = 0; u < 2; ++u) {
;                             const f32x4 pr = q[i][u] * kx[t][u];
;                             const float s = row16_sum((pr[0] + pr[1]) + (pr[2] + pr[3]));
;                             const float mn = fmaxf(m[i][u], s), scl = __builtin_amdgcn_exp2f(m[i][u] - mn), p = fm * __builtin_amdgcn_exp2f(s - mn);
;                             m[i][u] = mn; l[i][u] = l[i][u] * scl + p; o[i][u] = o[i][u] * scl + vx[t][u] * p;
;                         }
;                     }
;                 }
.LBB0_1117:
	v_pk_mul_f32 v[68:69], v[66:67], v[110:111]
	v_pk_mul_f32 v[70:71], v[64:65], v[108:109]
	v_pk_mul_f32 v[74:75], v[58:59], v[114:115]
	v_pk_mov_b32 v[72:73], v[70:71], v[68:69] op_sel:[1,0]
	v_mov_b32_e32 v71, v69
	v_pk_add_f32 v[68:69], v[72:73], v[70:71]
	v_pk_mul_f32 v[76:77], v[56:57], v[112:113]
	v_add_f32_e32 v3, v68, v69
	v_max_f32_e32 v68, v173, v173
	v_pk_mov_b32 v[78:79], v[76:77], v[74:75] op_sel:[1,0]
	v_add_f32_dpp v3, v3, v3 quad_perm:[1,0,3,2] row_mask:0xf bank_mask:0xf bound_ctrl:1
	v_mov_b32_e32 v77, v75
	v_pk_add_f32 v[74:75], v[78:79], v[76:77]
	v_add_f32_dpp v3, v3, v3 quad_perm:[2,3,0,1] row_mask:0xf bank_mask:0xf bound_ctrl:1
	v_max_f32_e32 v71, v159, v159
	s_nop 0
	v_add_f32_dpp v3, v3, v3 row_half_mirror row_mask:0xf bank_mask:0xf bound_ctrl:1
	s_nop 1
	v_add_f32_dpp v3, v3, v3 row_ror:8 row_mask:0xf bank_mask:0xf bound_ctrl:1
	v_max_f32_e32 v175, v68, v3
	v_sub_f32_e32 v3, v3, v175
	v_exp_f32_e32 v68, v3
	v_add_f32_e32 v3, v74, v75
	v_sub_f32_e32 v69, v173, v175
	v_exp_f32_e32 v70, v69
	v_add_f32_dpp v3, v3, v3 quad_perm:[1,0,3,2] row_mask:0xf bank_mask:0xf bound_ctrl:1
	v_mov_b32_e32 v174, v68
	v_pk_mul_f32 v[72:73], v[60:61], v[68:69] op_sel_hi:[1,0]
	v_add_f32_dpp v3, v3, v3 quad_perm:[2,3,0,1] row_mask:0xf bank_mask:0xf bound_ctrl:1
	v_pk_mul_f32 v[68:69], v[62:63], v[68:69] op_sel_hi:[1,0]
	v_fmac_f32_e32 v174, v172, v70
	v_add_f32_dpp v3, v3, v3 row_half_mirror row_mask:0xf bank_mask:0xf bound_ctrl:1
	v_mov_b32_e32 v172, v174
	v_mov_b32_e32 v173, v175
	v_add_f32_dpp v3, v3, v3 row_ror:8 row_mask:0xf bank_mask:0xf bound_ctrl:1
	v_max_f32_e32 v179, v71, v3
	v_sub_f32_e32 v3, v3, v179
	v_sub_f32_e32 v71, v159, v179
	v_exp_f32_e32 v74, v3
	v_exp_f32_e32 v76, v71
	v_pk_fma_f32 v[34:35], v[34:35], v[70:71], v[68:69] op_sel_hi:[1,0,1]
	v_pk_fma_f32 v[32:33], v[32:33], v[70:71], v[72:73] op_sel_hi:[1,0,1]
	v_mov_b32_e32 v178, v74
	v_fmac_f32_e32 v178, v158, v76
	v_pk_mul_f32 v[68:69], v[52:53], v[74:75] op_sel_hi:[1,0]
	v_pk_mul_f32 v[70:71], v[54:55], v[74:75] op_sel_hi:[1,0]
	v_pk_fma_f32 v[28:29], v[28:29], v[76:77], v[68:69] op_sel_hi:[1,0,1]
	v_pk_fma_f32 v[30:31], v[30:31], v[76:77], v[70:71] op_sel_hi:[1,0,1]
	v_mov_b32_e32 v158, v178
	v_mov_b32_e32 v159, v179
	s_cmp_lt_i32 s2, 2
	v_mov_b32_e32 v3, 0
	s_cbranch_scc0 .LBB0_1115

; __device__ __forceinline__ float row16_sum(float v) { v += dppf<0xB1>(v); v += dppf<0x4E>(v); v += dppf<0x141>(v); v += dppf<0x128>(v); return v; }
; __device__ __forceinline__ void attn_sample_phase(const bf16* QKVb, const float* ck, const float* cv, const float* out, bf16* SPART, float2* SML, int gw, int NGW, int lane) {
;     ...
; #pragma unroll
;             for (int t = 0; t < 4; ++t)
; #pragma unroll
;                 for (int i = 0; i < 4; ++i) {
;                     const int dl = ee[t] - 3 + i;
;                     const int mult = dl >= 0 ? (int)(dl <= 128) + (int)(((dl & 3) == 0) && dl <= 512) + (int)(((dl & 15) == 0) && dl <= 2048) : 0;
;                     if (mult) {
;                         const float fm = (float)mult;
; #pragma unroll
;                         for (int u = 0; u < 2; ++u) {
;                             const f32x4 pr = q[i][u] * kx[t][u];
;                             const float s = row16_sum((pr[0] + pr[1]) + (pr[2] + pr[3]));
;                             const float mn = fmaxf(m[i][u], s), scl = __builtin_amdgcn_exp2f(m[i][u] - mn), p = fm * __builtin_amdgcn_exp2f(s - mn);
;                             m[i][u] = mn; l[i][u] = l[i][u] * scl + p; o[i][u] = o[i][u] * scl + vx[t][u] * p;
;                         }
;                     }
;                 }
.LBB0_1119:
	v_pk_mul_f32 v[68:69], v[66:67], v[118:119]
	v_pk_mul_f32 v[70:71], v[64:65], v[116:117]
	s_nop 0
	v_pk_mov_b32 v[72:73], v[70:71], v[68:69] op_sel:[1,0]
	v_mov_b32_e32 v71, v69
	v_pk_add_f32 v[68:69], v[72:73], v[70:71]
	v_cvt_f32_ubyte0_e32 v71, v3
	v_add_f32_e32 v68, v68, v69
	v_max_f32_e32 v69, v171, v171
	s_nop 0
	v_add_f32_dpp v68, v68, v68 quad_perm:[1,0,3,2] row_mask:0xf bank_mask:0xf bound_ctrl:1
	s_nop 1
	v_add_f32_dpp v68, v68, v68 quad_perm:[2,3,0,1] row_mask:0xf bank_mask:0xf bound_ctrl:1
	s_nop 1
	v_add_f32_dpp v68, v68, v68 row_half_mirror row_mask:0xf bank_mask:0xf bound_ctrl:1
	s_nop 1
	v_add_f32_dpp v68, v68, v68 row_ror:8 row_mask:0xf bank_mask:0xf bound_ctrl:1
	v_max_f32_e32 v69, v69, v68
	v_sub_f32_e32 v70, v171, v69
	v_sub_f32_e32 v68, v68, v69
	v_exp_f32_e32 v70, v70
	v_exp_f32_e32 v177, v68
	v_max_f32_e32 v68, v155, v155
	v_mov_b32_e32 v171, v69
	v_pk_mul_f32 v[72:73], v[176:177], v[70:71]
	v_pk_mul_f32 v[74:75], v[60:61], v[72:73] op_sel:[0,1]
	v_pk_mul_f32 v[76:77], v[62:63], v[72:73] op_sel:[0,1]
	v_pk_fma_f32 v[24:25], v[24:25], v[70:71], v[74:75] op_sel_hi:[1,0,1]
	v_pk_fma_f32 v[26:27], v[26:27], v[70:71], v[76:77] op_sel_hi:[1,0,1]
	v_pk_mul_f32 v[74:75], v[58:59], v[122:123]
	v_pk_mul_f32 v[76:77], v[56:57], v[120:121]
	s_nop 0
	v_pk_mov_b32 v[78:79], v[76:77], v[74:75] op_sel:[1,0]
	v_mov_b32_e32 v77, v75
	v_pk_add_f32 v[74:75], v[78:79], v[76:77]
	s_nop 0
	v_add_f32_e32 v3, v74, v75
	s_nop 1
	v_add_f32_dpp v3, v3, v3 quad_perm:[1,0,3,2] row_mask:0xf bank_mask:0xf bound_ctrl:1
	s_nop 1
	v_add_f32_dpp v3, v3, v3 quad_perm:[2,3,0,1] row_mask:0xf bank_mask:0xf bound_ctrl:1
	s_nop 1
	v_add_f32_dpp v3, v3, v3 row_half_mirror row_mask:0xf bank_mask:0xf bound_ctrl:1
	s_nop 1
	v_add_f32_dpp v3, v3, v3 row_ror:8 row_mask:0xf bank_mask:0xf bound_ctrl:1
	v_max_f32_e32 v75, v68, v3
	v_sub_f32_e32 v68, v155, v75
	v_sub_f32_e32 v3, v3, v75
	v_exp_f32_e32 v70, v68
	v_exp_f32_e32 v183, v3
	v_add_f32_e32 v68, v72, v73
	v_mov_b64_e32 v[176:177], v[68:69]
	v_mov_b32_e32 v170, v68
	v_pk_mul_f32 v[76:77], v[182:183], v[70:71]
	v_mov_b32_e32 v155, v75
	v_pk_mul_f32 v[78:79], v[52:53], v[76:77] op_sel:[0,1]
	v_pk_mul_f32 v[80:81], v[54:55], v[76:77] op_sel:[0,1]
	v_add_f32_e32 v74, v76, v77
	v_pk_fma_f32 v[22:23], v[22:23], v[70:71], v[80:81] op_sel_hi:[1,0,1]
	v_pk_fma_f32 v[20:21], v[20:21], v[70:71], v[78:79] op_sel_hi:[1,0,1]
	v_mov_b64_e32 v[182:183], v[74:75]
	v_mov_b32_e32 v154, v74
.LBB0_1120:
	s_cmpk_gt_u32 s2, 0x81
	s_cbranch_scc1 .LBB0_1124
	v_pk_mul_f32 v[68:69], v[66:67], v[126:127]
	v_pk_mul_f32 v[70:71], v[64:65], v[124:125]
	v_pk_mul_f32 v[74:75], v[58:59], v[142:143]
	v_pk_mov_b32 v[72:73], v[70:71], v[68:69] op_sel:[1,0]
	v_mov_b32_e32 v71, v69
	v_pk_add_f32 v[68:69], v[72:73], v[70:71]
	v_pk_mul_f32 v[76:77], v[56:57], v[128:129]
	v_add_f32_e32 v3, v68, v69
	v_max_f32_e32 v68, v169, v169
	v_pk_mov_b32 v[78:79], v[76:77], v[74:75] op_sel:[1,0]
	v_add_f32_dpp v3, v3, v3 quad_perm:[1,0,3,2] row_mask:0xf bank_mask:0xf bound_ctrl:1
	v_mov_b32_e32 v77, v75
	v_pk_add_f32 v[74:75], v[78:79], v[76:77]
	v_add_f32_dpp v3, v3, v3 quad_perm:[2,3,0,1] row_mask:0xf bank_mask:0xf bound_ctrl:1
	v_max_f32_e32 v71, v153, v153
	s_nop 0
	v_add_f32_dpp v3, v3, v3 row_half_mirror row_mask:0xf bank_mask:0xf bound_ctrl:1
	s_nop 1
	v_add_f32_dpp v3, v3, v3 row_ror:8 row_mask:0xf bank_mask:0xf bound_ctrl:1
	v_max_f32_e32 v181, v68, v3
	v_sub_f32_e32 v3, v3, v181
	v_exp_f32_e32 v68, v3
	v_add_f32_e32 v3, v74, v75
	v_sub_f32_e32 v69, v169, v181
	v_exp_f32_e32 v70, v69
	v_add_f32_dpp v3, v3, v3 quad_perm:[1,0,3,2] row_mask:0xf bank_mask:0xf bound_ctrl:1
	v_mov_b32_e32 v180, v68
	v_pk_mul_f32 v[72:73], v[60:61], v[68:69] op_sel_hi:[1,0]
	v_add_f32_dpp v3, v3, v3 quad_perm:[2,3,0,1] row_mask:0xf bank_mask:0xf bound_ctrl:1
	v_pk_mul_f32 v[68:69], v[62:63], v[68:69] op_sel_hi:[1,0]
	v_fmac_f32_e32 v180, v168, v70
	v_add_f32_dpp v3, v3, v3 row_half_mirror row_mask:0xf bank_mask:0xf bound_ctrl:1
	v_mov_b32_e32 v168, v180
	v_mov_b32_e32 v169, v181
	v_add_f32_dpp v3, v3, v3 row_ror:8 row_mask:0xf bank_mask:0xf bound_ctrl:1
	v_max_f32_e32 v185, v71, v3
	v_sub_f32_e32 v3, v3, v185
	v_sub_f32_e32 v71, v153, v185
	v_exp_f32_e32 v74, v3
	v_exp_f32_e32 v76, v71
	v_pk_fma_f32 v[18:19], v[18:19], v[70:71], v[68:69] op_sel_hi:[1,0,1]
	v_pk_fma_f32 v[16:17], v[16:17], v[70:71], v[72:73] op_sel_hi:[1,0,1]
	v_mov_b32_e32 v184, v74
	v_fmac_f32_e32 v184, v152, v76
	v_pk_mul_f32 v[68:69], v[52:53], v[74:75] op_sel_hi:[1,0]
	v_pk_mul_f32 v[70:71], v[54:55], v[74:75] op_sel_hi:[1,0]
	v_pk_fma_f32 v[12:13], v[12:13], v[76:77], v[68:69] op_sel_hi:[1,0,1]
	v_pk_fma_f32 v[14:15], v[14:15], v[76:77], v[70:71] op_sel_hi:[1,0,1]
	v_mov_b32_e32 v152, v184
	v_mov_b32_e32 v153, v185
	s_cmpk_gt_u32 s2, 0x80
	s_cbranch_scc0 .LBB0_1125

; __device__ __forceinline__ void attn_sample_phase(const bf16* QKVb, const float* ck, const float* cv, const float* out, bf16* SPART, float2* SML, int gw, int NGW, int lane) {
;     ...
;                     const int dl = ee[t] - 3 + i;
;                     const int mult = dl >= 0 ? (int)(dl <= 128) + (int)(((dl & 3) == 0) && dl <= 512) + (int)(((dl & 15) == 0) && dl <= 2048) : 0;
.LBB0_1123:
	s_add_i32 s8, s26, -3
	s_cmpk_lt_u32 s8, 0x81
	s_cselect_b64 s[2:3], -1, 0
	s_cmpk_lt_u32 s8, 0x201
	v_cndmask_b32_e64 v3, 0, 1, s[2:3]
	s_cselect_b64 s[2:3], -1, 0
	v_cndmask_b32_e64 v52, 0, 1, s[2:3]
	s_and_b32 s2, s8, 12
	s_cmp_eq_u32 s2, 0
	s_cselect_b64 s[2:3], -1, 0
	s_cmpk_lt_u32 s8, 0x801
	s_cselect_b64 s[8:9], -1, 0
	s_and_b64 vcc, s[8:9], s[2:3]
	v_addc_co_u32_e32 v3, vcc, v52, v3, vcc
	v_cmp_eq_u32_e32 vcc, 0, v3
	s_cbranch_vccz .LBB0_1127
	s_branch .LBB0_1128

; __device__ __forceinline__ float row16_sum(float v) { v += dppf<0xB1>(v); v += dppf<0x4E>(v); v += dppf<0x141>(v); v += dppf<0x128>(v); return v; }
; __device__ __forceinline__ void attn_sample_phase(const bf16* QKVb, const float* ck, const float* cv, const float* out, bf16* SPART, float2* SML, int gw, int NGW, int lane) {
;     ...
; #pragma unroll
;             for (int t = 0; t < 4; ++t)
; #pragma unroll
;                 for (int i = 0; i < 4; ++i) {
;                     const int dl = ee[t] - 3 + i;
;                     const int mult = dl >= 0 ? (int)(dl <= 128) + (int)(((dl & 3) == 0) && dl <= 512) + (int)(((dl & 15) == 0) && dl <= 2048) : 0;
;                     if (mult) {
;                         const float fm = (float)mult;
; #pragma unroll
;                         for (int u = 0; u < 2; ++u) {
;                             const f32x4 pr = q[i][u] * kx[t][u];
;                             const float s = row16_sum((pr[0] + pr[1]) + (pr[2] + pr[3]));
;                             const float mn = fmaxf(m[i][u], s), scl = __builtin_amdgcn_exp2f(m[i][u] - mn), p = fm * __builtin_amdgcn_exp2f(s - mn);
;                             m[i][u] = mn; l[i][u] = l[i][u] * scl + p; o[i][u] = o[i][u] * scl + vx[t][u] * p;
;                         }
;                     }
;                 }
.LBB0_1125:
	v_pk_mul_f32 v[66:67], v[66:67], v[146:147]
	v_pk_mul_f32 v[64:65], v[64:65], v[144:145]
	v_pk_mul_f32 v[58:59], v[58:59], v[150:151]
	v_pk_mov_b32 v[68:69], v[64:65], v[66:67] op_sel:[1,0]
	v_mov_b32_e32 v65, v67
	v_pk_add_f32 v[64:65], v[68:69], v[64:65]
	v_pk_mul_f32 v[56:57], v[56:57], v[148:149]
	v_add_f32_e32 v3, v64, v65
	v_max_f32_e32 v64, v97, v97
	s_nop 0
	v_add_f32_dpp v3, v3, v3 quad_perm:[1,0,3,2] row_mask:0xf bank_mask:0xf bound_ctrl:1
	s_nop 1
	v_add_f32_dpp v3, v3, v3 quad_perm:[2,3,0,1] row_mask:0xf bank_mask:0xf bound_ctrl:1
	s_nop 1
	v_add_f32_dpp v3, v3, v3 row_half_mirror row_mask:0xf bank_mask:0xf bound_ctrl:1
	s_nop 1
	v_add_f32_dpp v3, v3, v3 row_ror:8 row_mask:0xf bank_mask:0xf bound_ctrl:1
	v_max_f32_e32 v157, v64, v3
	v_sub_f32_e32 v3, v3, v157
	v_exp_f32_e32 v64, v3
	v_sub_f32_e32 v65, v97, v157
	v_exp_f32_e32 v66, v65
	v_mov_b32_e32 v97, v157
	v_mov_b32_e32 v156, v64
	v_pk_mul_f32 v[60:61], v[60:61], v[64:65] op_sel_hi:[1,0]
	v_pk_mul_f32 v[62:63], v[62:63], v[64:65] op_sel_hi:[1,0]
	v_pk_mov_b32 v[64:65], v[56:57], v[58:59] op_sel:[1,0]
	v_mov_b32_e32 v57, v59
	v_pk_add_f32 v[56:57], v[64:65], v[56:57]
	v_fmac_f32_e32 v156, v96, v66
	v_add_f32_e32 v3, v56, v57
	v_max_f32_e32 v56, v89, v89
	v_pk_fma_f32 v[10:11], v[10:11], v[66:67], v[62:63] op_sel_hi:[1,0,1]
	v_add_f32_dpp v3, v3, v3 quad_perm:[1,0,3,2] row_mask:0xf bank_mask:0xf bound_ctrl:1
	v_pk_fma_f32 v[8:9], v[8:9], v[66:67], v[60:61] op_sel_hi:[1,0,1]
	v_mov_b32_e32 v96, v156
	v_add_f32_dpp v3, v3, v3 quad_perm:[2,3,0,1] row_mask:0xf bank_mask:0xf bound_ctrl:1
	s_nop 1
	v_add_f32_dpp v3, v3, v3 row_half_mirror row_mask:0xf bank_mask:0xf bound_ctrl:1
	s_nop 1
	v_add_f32_dpp v3, v3, v3 row_ror:8 row_mask:0xf bank_mask:0xf bound_ctrl:1
	v_max_f32_e32 v161, v56, v3
	v_sub_f32_e32 v3, v3, v161
	v_sub_f32_e32 v57, v89, v161
	v_exp_f32_e32 v56, v3
	v_exp_f32_e32 v58, v57
	v_mov_b32_e32 v89, v161
	v_mov_b32_e32 v160, v56
	v_fmac_f32_e32 v160, v88, v58
	v_pk_mul_f32 v[52:53], v[52:53], v[56:57] op_sel_hi:[1,0]
	v_pk_mul_f32 v[54:55], v[54:55], v[56:57] op_sel_hi:[1,0]
	v_pk_fma_f32 v[4:5], v[4:5], v[58:59], v[52:53] op_sel_hi:[1,0,1]
	v_pk_fma_f32 v[6:7], v[6:7], v[58:59], v[54:55] op_sel_hi:[1,0,1]
	v_mov_b32_e32 v88, v160
	s_cmp_lt_i32 s26, 3
	v_mov_b32_e32 v3, 0
	s_cbranch_scc0 .LBB0_1123

; __device__ __forceinline__ float row16_sum(float v) { v += dppf<0xB1>(v); v += dppf<0x4E>(v); v += dppf<0x141>(v); v += dppf<0x128>(v); return v; }
; __device__ __forceinline__ void attn_sample_phase(const bf16* QKVb, const float* ck, const float* cv, const float* out, bf16* SPART, float2* SML, int gw, int NGW, int lane) {
;     ...
; #pragma unroll
;             for (int t = 0; t < 4; ++t)
; #pragma unroll
;                 for (int i = 0; i < 4; ++i) {
;                     const int dl = ee[t] - 3 + i;
;                     const int mult = dl >= 0 ? (int)(dl <= 128) + (int)(((dl & 3) == 0) && dl <= 512) + (int)(((dl & 15) == 0) && dl <= 2048) : 0;
;                     if (mult) {
;                         const float fm = (float)mult;
; #pragma unroll
;                         for (int u = 0; u < 2; ++u) {
;                             const f32x4 pr = q[i][u] * kx[t][u];
;                             const float s = row16_sum((pr[0] + pr[1]) + (pr[2] + pr[3]));
;                             const float mn = fmaxf(m[i][u], s), scl = __builtin_amdgcn_exp2f(m[i][u] - mn), p = fm * __builtin_amdgcn_exp2f(s - mn);
;                             m[i][u] = mn; l[i][u] = l[i][u] * scl + p; o[i][u] = o[i][u] * scl + vx[t][u] * p;
;                         }
;                     }
;                 }
.LBB0_1127:
	v_pk_mul_f32 v[52:53], v[50:51], v[110:111]
	v_pk_mul_f32 v[54:55], v[48:49], v[108:109]
	s_nop 0
	v_pk_mov_b32 v[56:57], v[54:55], v[52:53] op_sel:[1,0]
	v_mov_b32_e32 v55, v53
	v_pk_add_f32 v[52:53], v[56:57], v[54:55]
	v_cvt_f32_ubyte0_e32 v55, v3
	v_add_f32_e32 v52, v52, v53
	v_max_f32_e32 v53, v173, v173
	s_nop 0
	v_add_f32_dpp v52, v52, v52 quad_perm:[1,0,3,2] row_mask:0xf bank_mask:0xf bound_ctrl:1
	s_nop 1
	v_add_f32_dpp v52, v52, v52 quad_perm:[2,3,0,1] row_mask:0xf bank_mask:0xf bound_ctrl:1
	s_nop 1
	v_add_f32_dpp v52, v52, v52 row_half_mirror row_mask:0xf bank_mask:0xf bound_ctrl:1
	s_nop 1
	v_add_f32_dpp v52, v52, v52 row_ror:8 row_mask:0xf bank_mask:0xf bound_ctrl:1
	v_max_f32_e32 v53, v53, v52
	v_sub_f32_e32 v54, v173, v53
	v_sub_f32_e32 v52, v52, v53
	v_exp_f32_e32 v54, v54
	v_exp_f32_e32 v175, v52
	v_max_f32_e32 v52, v159, v159
	v_mov_b32_e32 v173, v53
	v_pk_mul_f32 v[56:57], v[174:175], v[54:55]
	v_pk_mul_f32 v[58:59], v[44:45], v[56:57] op_sel:[0,1]
	v_pk_mul_f32 v[60:61], v[46:47], v[56:57] op_sel:[0,1]
	v_pk_fma_f32 v[32:33], v[32:33], v[54:55], v[58:59] op_sel_hi:[1,0,1]
	v_pk_fma_f32 v[34:35], v[34:35], v[54:55], v[60:61] op_sel_hi:[1,0,1]
	v_pk_mul_f32 v[58:59], v[42:43], v[114:115]
	v_pk_mul_f32 v[60:61], v[40:41], v[112:113]
	s_nop 0
	v_pk_mov_b32 v[62:63], v[60:61], v[58:59] op_sel:[1,0]
	v_mov_b32_e32 v61, v59
	v_pk_add_f32 v[58:59], v[62:63], v[60:61]
	s_nop 0
	v_add_f32_e32 v3, v58, v59
	s_nop 1
	v_add_f32_dpp v3, v3, v3 quad_perm:[1,0,3,2] row_mask:0xf bank_mask:0xf bound_ctrl:1
	s_nop 1
	v_add_f32_dpp v3, v3, v3 quad_perm:[2,3,0,1] row_mask:0xf bank_mask:0xf bound_ctrl:1
	s_nop 1
	v_add_f32_dpp v3, v3, v3 row_half_mirror row_mask:0xf bank_mask:0xf bound_ctrl:1
	s_nop 1
	v_add_f32_dpp v3, v3, v3 row_ror:8 row_mask:0xf bank_mask:0xf bound_ctrl:1
	v_max_f32_e32 v59, v52, v3
	v_sub_f32_e32 v52, v159, v59
	v_sub_f32_e32 v3, v3, v59
	v_exp_f32_e32 v54, v52
	v_exp_f32_e32 v179, v3
	v_add_f32_e32 v52, v56, v57
	v_mov_b64_e32 v[174:175], v[52:53]
	v_mov_b32_e32 v172, v52
	v_pk_mul_f32 v[60:61], v[178:179], v[54:55]
	v_mov_b32_e32 v159, v59
	v_pk_mul_f32 v[62:63], v[36:37], v[60:61] op_sel:[0,1]
	v_pk_mul_f32 v[64:65], v[38:39], v[60:61] op_sel:[0,1]
	v_add_f32_e32 v58, v60, v61
	v_pk_fma_f32 v[30:31], v[30:31], v[54:55], v[64:65] op_sel_hi:[1,0,1]
	v_pk_fma_f32 v[28:29], v[28:29], v[54:55], v[62:63] op_sel_hi:[1,0,1]
	v_mov_b64_e32 v[178:179], v[58:59]
	v_mov_b32_e32 v158, v58
.LBB0_1128:
	s_cmpk_gt_u32 s26, 0x82
	s_cbranch_scc1 .LBB0_1131
	v_pk_mul_f32 v[52:53], v[50:51], v[118:119]
	v_pk_mul_f32 v[54:55], v[48:49], v[116:117]
	v_pk_mul_f32 v[58:59], v[42:43], v[122:123]
	v_pk_mov_b32 v[56:57], v[54:55], v[52:53] op_sel:[1,0]
	v_mov_b32_e32 v55, v53
	v_pk_add_f32 v[52:53], v[56:57], v[54:55]
	v_pk_mul_f32 v[60:61], v[40:41], v[120:121]
	v_add_f32_e32 v3, v52, v53
	v_max_f32_e32 v52, v171, v171
	v_pk_mov_b32 v[62:63], v[60:61], v[58:59] op_sel:[1,0]
	v_add_f32_dpp v3, v3, v3 quad_perm:[1,0,3,2] row_mask:0xf bank_mask:0xf bound_ctrl:1
	v_mov_b32_e32 v61, v59
	v_pk_add_f32 v[58:59], v[62:63], v[60:61]
	v_add_f32_dpp v3, v3, v3 quad_perm:[2,3,0,1] row_mask:0xf bank_mask:0xf bound_ctrl:1
	v_max_f32_e32 v55, v155, v155
	s_nop 0
	v_add_f32_dpp v3, v3, v3 row_half_mirror row_mask:0xf bank_mask:0xf bound_ctrl:1
	s_nop 1
	v_add_f32_dpp v3, v3, v3 row_ror:8 row_mask:0xf bank_mask:0xf bound_ctrl:1
	v_max_f32_e32 v177, v52, v3
	v_sub_f32_e32 v3, v3, v177
	v_exp_f32_e32 v52, v3
	v_add_f32_e32 v3, v58, v59
	v_sub_f32_e32 v53, v171, v177
	v_exp_f32_e32 v54, v53
	v_add_f32_dpp v3, v3, v3 quad_perm:[1,0,3,2] row_mask:0xf bank_mask:0xf bound_ctrl:1
	v_mov_b32_e32 v176, v52
	v_pk_mul_f32 v[56:57], v[44:45], v[52:53] op_sel_hi:[1,0]
	v_add_f32_dpp v3, v3, v3 quad_perm:[2,3,0,1] row_mask:0xf bank_mask:0xf bound_ctrl:1
	v_pk_mul_f32 v[52:53], v[46:47], v[52:53] op_sel_hi:[1,0]
	v_fmac_f32_e32 v176, v170, v54
	v_add_f32_dpp v3, v3, v3 row_half_mirror row_mask:0xf bank_mask:0xf bound_ctrl:1
	v_mov_b32_e32 v170, v176
	v_mov_b32_e32 v171, v177
	v_add_f32_dpp v3, v3, v3 row_ror:8 row_mask:0xf bank_mask:0xf bound_ctrl:1
	v_max_f32_e32 v183, v55, v3
	v_sub_f32_e32 v3, v3, v183
	v_sub_f32_e32 v55, v155, v183
	v_exp_f32_e32 v58, v3
	v_exp_f32_e32 v60, v55
	v_pk_fma_f32 v[26:27], v[26:27], v[54:55], v[52:53] op_sel_hi:[1,0,1]
	v_pk_fma_f32 v[24:25], v[24:25], v[54:55], v[56:57] op_sel_hi:[1,0,1]
	v_mov_b32_e32 v182, v58
	v_fmac_f32_e32 v182, v154, v60
	v_pk_mul_f32 v[52:53], v[36:37], v[58:59] op_sel_hi:[1,0]
	v_pk_mul_f32 v[54:55], v[38:39], v[58:59] op_sel_hi:[1,0]
	v_pk_fma_f32 v[20:21], v[20:21], v[60:61], v[52:53] op_sel_hi:[1,0,1]
	v_pk_fma_f32 v[22:23], v[22:23], v[60:61], v[54:55] op_sel_hi:[1,0,1]
	v_mov_b32_e32 v154, v182
	v_mov_b32_e32 v155, v183
	s_cmpk_gt_u32 s26, 0x81
	s_cbranch_scc0 .LBB0_1132

; __device__ __forceinline__ float row16_sum(float v) { v += dppf<0xB1>(v); v += dppf<0x4E>(v); v += dppf<0x141>(v); v += dppf<0x128>(v); return v; }
; __device__ __forceinline__ void attn_sample_phase(const bf16* QKVb, const float* ck, const float* cv, const float* out, bf16* SPART, float2* SML, int gw, int NGW, int lane) {
;     ...
; #pragma unroll
;             for (int t = 0; t < 4; ++t)
; #pragma unroll
;                 for (int i = 0; i < 4; ++i) {
;                     const int dl = ee[t] - 3 + i;
;                     const int mult = dl >= 0 ? (int)(dl <= 128) + (int)(((dl & 3) == 0) && dl <= 512) + (int)(((dl & 15) == 0) && dl <= 2048) : 0;
;                     if (mult) {
;                         const float fm = (float)mult;
; #pragma unroll
;                         for (int u = 0; u < 2; ++u) {
;                             const f32x4 pr = q[i][u] * kx[t][u];
;                             const float s = row16_sum((pr[0] + pr[1]) + (pr[2] + pr[3]));
;                             const float mn = fmaxf(m[i][u], s), scl = __builtin_amdgcn_exp2f(m[i][u] - mn), p = fm * __builtin_amdgcn_exp2f(s - mn);
;                             m[i][u] = mn; l[i][u] = l[i][u] * scl + p; o[i][u] = o[i][u] * scl + vx[t][u] * p;
;                         }
;                     }
;                 }
.LBB0_1132:
	v_pk_mul_f32 v[52:53], v[50:51], v[126:127]
	v_pk_mul_f32 v[54:55], v[48:49], v[124:125]
	v_pk_mul_f32 v[58:59], v[42:43], v[142:143]
	v_pk_mov_b32 v[56:57], v[54:55], v[52:53] op_sel:[1,0]
	v_mov_b32_e32 v55, v53
	v_pk_add_f32 v[52:53], v[56:57], v[54:55]
	v_pk_mul_f32 v[60:61], v[40:41], v[128:129]
	v_add_f32_e32 v3, v52, v53
	v_max_f32_e32 v52, v169, v169
	v_pk_mov_b32 v[62:63], v[60:61], v[58:59] op_sel:[1,0]
	v_add_f32_dpp v3, v3, v3 quad_perm:[1,0,3,2] row_mask:0xf bank_mask:0xf bound_ctrl:1
	v_mov_b32_e32 v61, v59
	v_pk_add_f32 v[58:59], v[62:63], v[60:61]
	v_add_f32_dpp v3, v3, v3 quad_perm:[2,3,0,1] row_mask:0xf bank_mask:0xf bound_ctrl:1
	v_max_f32_e32 v55, v153, v153
	s_nop 0
	v_add_f32_dpp v3, v3, v3 row_half_mirror row_mask:0xf bank_mask:0xf bound_ctrl:1
	s_nop 1
	v_add_f32_dpp v3, v3, v3 row_ror:8 row_mask:0xf bank_mask:0xf bound_ctrl:1
	v_max_f32_e32 v181, v52, v3
	v_sub_f32_e32 v3, v3, v181
	v_exp_f32_e32 v52, v3
	v_add_f32_e32 v3, v58, v59
	v_sub_f32_e32 v53, v169, v181
	v_exp_f32_e32 v54, v53
	v_add_f32_dpp v3, v3, v3 quad_perm:[1,0,3,2] row_mask:0xf bank_mask:0xf bound_ctrl:1
	v_mov_b32_e32 v180, v52
	v_pk_mul_f32 v[56:57], v[44:45], v[52:53] op_sel_hi:[1,0]
	v_add_f32_dpp v3, v3, v3 quad_perm:[2,3,0,1] row_mask:0xf bank_mask:0xf bound_ctrl:1
	v_pk_mul_f32 v[52:53], v[46:47], v[52:53] op_sel_hi:[1,0]
	v_fmac_f32_e32 v180, v168, v54
	v_add_f32_dpp v3, v3, v3 row_half_mirror row_mask:0xf bank_mask:0xf bound_ctrl:1
	v_mov_b32_e32 v168, v180
	v_mov_b32_e32 v169, v181
	v_add_f32_dpp v3, v3, v3 row_ror:8 row_mask:0xf bank_mask:0xf bound_ctrl:1
	v_max_f32_e32 v185, v55, v3
	v_sub_f32_e32 v3, v3, v185
	v_sub_f32_e32 v55, v153, v185
	v_exp_f32_e32 v58, v3
	v_exp_f32_e32 v60, v55
	v_pk_fma_f32 v[18:19], v[18:19], v[54:55], v[52:53] op_sel_hi:[1,0,1]
	v_pk_fma_f32 v[16:17], v[16:17], v[54:55], v[56:57] op_sel_hi:[1,0,1]
	v_mov_b32_e32 v184, v58
	v_fmac_f32_e32 v184, v152, v60
	v_pk_mul_f32 v[52:53], v[36:37], v[58:59] op_sel_hi:[1,0]
	v_pk_mul_f32 v[54:55], v[38:39], v[58:59] op_sel_hi:[1,0]
	v_pk_fma_f32 v[12:13], v[12:13], v[60:61], v[52:53] op_sel_hi:[1,0,1]
	v_pk_fma_f32 v[14:15], v[14:15], v[60:61], v[54:55] op_sel_hi:[1,0,1]
	v_mov_b32_e32 v152, v184
	v_mov_b32_e32 v153, v185
	s_cmpk_gt_u32 s26, 0x80
	s_cbranch_scc0 .LBB0_1077
.LBB0_1133:
	v_mov_b64_e32 v[48:49], v[156:157]
	v_mov_b64_e32 v[40:41], v[160:161]
	v_mov_b32_e32 v156, v96
	v_mov_b32_e32 v157, v97
	v_mov_b32_e32 v160, v88
	v_mov_b32_e32 v161, v89
	s_add_i32 s1, s1, 4
	s_add_i32 s25, s25, 16
	s_cmp_eq_u32 s1, 60
	s_cbranch_scc0 .LBB0_1078
